# v80 plus removal of the redundant back-to-back s_setprio 0/1 pairs between the two MFMA blocks of each K-loop super-phase
# baseline (speedup 1.0000x reference)
; #define PG8_STAGE(bufoff, gbase, voff) do { _Pragma("unroll") for (int _i = 0; _i < 2; ++_i) \
;         __builtin_amdgcn_global_load_lds((const unsigned*)((const char*)(gbase) + (voff)[_i]), (PG8_LAS unsigned*)(lds + (bufoff) + ldsw + _i * 8192), 16, 0, 0); } while (0)
; #define PG8_LDA(dst, b, h) do { _Pragma("unroll") for (int m = 0; m < 4; ++m) _Pragma("unroll") for (int k = 0; k < 2; ++k) dst[m][k] = *(const PG8_LAS bf16x8*)(lds + PG8_SA(b, h) + aoff + m * 2048 + k * 1024); } while (0)
; #define PG8_LDB(dst, b, h) do { _Pragma("unroll") for (int n = 0; n < 2; ++n) _Pragma("unroll") for (int k = 0; k < 2; ++k) dst[n][k] = *(const PG8_LAS bf16x8*)(lds + PG8_SB(b, h) + boff + n * 2048 + k * 1024); } while (0)
; #define PG8_MMA(ai, bj, At, Bt) do { __builtin_amdgcn_s_setprio(1); _Pragma("unroll") for (int m = 0; m < 4; ++m) _Pragma("unroll") for (int n = 0; n < 2; ++n) _Pragma("unroll") for (int k = 0; k < 2; ++k) \
;         acc[ai][bj][m][n] = __builtin_amdgcn_mfma_f32_16x16x32_bf16(Bt[n][k], At[m][k], acc[ai][bj][m][n], 0, 0, 0); __builtin_amdgcn_s_setprio(0); } while (0)
; #define PG8_WAIT_V(n) asm volatile("s_waitcnt vmcnt(" #n ")" ::: "memory")
; #define PG8_WAIT_L(n) asm volatile("s_waitcnt lgkmcnt(" #n ")" ::: "memory")
; #define PG8_BAR __builtin_amdgcn_s_barrier()
; #define PG8_SCHED __builtin_amdgcn_sched_barrier(0)
; template <class Epi, class Sched, bool ALIGN_EPI = false, bool SP2 = false>
; __device__ __forceinline__ void gemm_phase(PG8_LAS unsigned char* lds, const Gemm g, const Sched& S, const Epi& E) {
;     ...
;             PG8_LDB(B0, 0, 0); PG8_LDB(B1, 0, 1); PG8_SCHED; PG8_LDA(At, 0, 0); PG8_STAGE(PG8_SA(1, 1), a1 + hstep, voffA);
;             PG8_WAIT_V(8); PG8_WAIT_L(0); PG8_BAR; PG8_MMA(0, 0, At, B0); PG8_MMA(0, 1, At, B1); PG8_BAR; PG8_SCHED;
;             PG8_LDA(At, 0, 1); PG8_STAGE(PG8_SB(0, 0), b2, voffB); PG8_STAGE(PG8_SB(0, 1), b2 + hstep, voffB); PG8_STAGE(PG8_SA(0, 0), a2, voffA);
;             PG8_WAIT_V(8); PG8_WAIT_L(0); PG8_BAR; PG8_MMA(1, 0, At, B0); PG8_MMA(1, 1, At, B1); PG8_BAR; PG8_SCHED;
.LBB0_124:
	ds_read_b128 v[146:149], v157
	ds_read_b128 v[150:153], v157 offset:1024
	ds_read_b128 v[160:163], v157 offset:2048
	ds_read_b128 v[164:167], v157 offset:3072
	ds_read_b128 v[168:171], v158
	ds_read_b128 v[172:175], v158 offset:1024
	ds_read_b128 v[176:179], v158 offset:2048
	ds_read_b128 v[180:183], v158 offset:3072
	s_add_u32 s12, s78, 0xfffc0080
	s_addc_u32 s13, s79, -1
	s_cmp_eq_u32 s11, 12
	s_cselect_b32 s83, s3, s13
	s_cselect_b32 s82, s5, s12
	s_cselect_b32 s81, s7, s10
	s_cselect_b32 s80, s8, s9
	v_lshl_add_u64 v[218:219], s[78:79], 0, v[138:139]
	s_add_i32 m0, s87, 0xc000
	ds_read_b128 v[184:187], v159
	ds_read_b128 v[188:191], v159 offset:1024
	ds_read_b128 v[192:195], v159 offset:2048
	ds_read_b128 v[196:199], v159 offset:3072
	ds_read_b128 v[200:203], v159 offset:4096
	ds_read_b128 v[206:209], v159 offset:5120
	ds_read_b128 v[210:213], v159 offset:6144
	ds_read_b128 v[214:217], v159 offset:7168
	global_load_lds_dwordx4 v[218:219], off
	v_lshl_add_u64 v[218:219], s[78:79], 0, v[140:141]
	s_add_i32 m0, s87, 0xe000
	s_nop 0
	global_load_lds_dwordx4 v[218:219], off
	s_waitcnt vmcnt(8)
	s_waitcnt lgkmcnt(0)
	s_barrier
	s_setprio 1
	s_waitcnt lgkmcnt(0)
	v_mfma_f32_16x16x32_bf16 v[124:127], v[146:149], v[184:187], v[124:127]
	v_mfma_f32_16x16x32_bf16 v[120:123], v[160:163], v[184:187], v[120:123]
	v_mfma_f32_16x16x32_bf16 v[108:111], v[146:149], v[192:195], v[108:111]
	v_mfma_f32_16x16x32_bf16 v[104:107], v[160:163], v[192:195], v[104:107]
	v_mfma_f32_16x16x32_bf16 v[92:95], v[146:149], v[200:203], v[92:95]
	v_mfma_f32_16x16x32_bf16 v[88:91], v[160:163], v[200:203], v[88:91]
	v_mfma_f32_16x16x32_bf16 v[76:79], v[146:149], v[210:213], v[76:79]
	v_mfma_f32_16x16x32_bf16 v[72:75], v[160:163], v[210:213], v[72:75]
	v_mfma_f32_16x16x32_bf16 v[124:127], v[150:153], v[188:191], v[124:127]
	v_mfma_f32_16x16x32_bf16 v[120:123], v[164:167], v[188:191], v[120:123]
	v_mfma_f32_16x16x32_bf16 v[108:111], v[150:153], v[196:199], v[108:111]
	v_mfma_f32_16x16x32_bf16 v[104:107], v[164:167], v[196:199], v[104:107]
	v_mfma_f32_16x16x32_bf16 v[92:95], v[150:153], v[206:209], v[92:95]
	v_mfma_f32_16x16x32_bf16 v[88:91], v[164:167], v[206:209], v[88:91]
	v_mfma_f32_16x16x32_bf16 v[76:79], v[150:153], v[214:217], v[76:79]
	v_mfma_f32_16x16x32_bf16 v[72:75], v[164:167], v[214:217], v[72:75]
	v_mfma_f32_16x16x32_bf16 v[116:119], v[168:171], v[184:187], v[116:119]
	v_mfma_f32_16x16x32_bf16 v[112:115], v[176:179], v[184:187], v[112:115]
	v_mfma_f32_16x16x32_bf16 v[100:103], v[168:171], v[192:195], v[100:103]
	v_mfma_f32_16x16x32_bf16 v[96:99], v[176:179], v[192:195], v[96:99]
	v_mfma_f32_16x16x32_bf16 v[84:87], v[168:171], v[200:203], v[84:87]
	v_mfma_f32_16x16x32_bf16 v[80:83], v[176:179], v[200:203], v[80:83]
	v_mfma_f32_16x16x32_bf16 v[68:71], v[168:171], v[210:213], v[68:71]
	v_mfma_f32_16x16x32_bf16 v[64:67], v[176:179], v[210:213], v[64:67]
	v_mfma_f32_16x16x32_bf16 v[116:119], v[172:175], v[188:191], v[116:119]
	v_mfma_f32_16x16x32_bf16 v[112:115], v[180:183], v[188:191], v[112:115]
	v_mfma_f32_16x16x32_bf16 v[100:103], v[172:175], v[196:199], v[100:103]
	v_mfma_f32_16x16x32_bf16 v[96:99], v[180:183], v[196:199], v[96:99]
	v_mfma_f32_16x16x32_bf16 v[84:87], v[172:175], v[206:209], v[84:87]
	v_mfma_f32_16x16x32_bf16 v[80:83], v[180:183], v[206:209], v[80:83]
	v_mfma_f32_16x16x32_bf16 v[68:71], v[172:175], v[214:217], v[68:71]
	v_mfma_f32_16x16x32_bf16 v[64:67], v[180:183], v[214:217], v[64:67]
	s_setprio 0
	s_barrier
	s_add_i32 s12, s94, s86
	v_lshl_add_u64 v[218:219], s[80:81], 0, v[130:131]
	s_mov_b32 m0, s12
	ds_read_b128 v[184:187], v159 offset:16384
	ds_read_b128 v[188:191], v159 offset:17408
	ds_read_b128 v[192:195], v159 offset:18432
	ds_read_b128 v[196:199], v159 offset:19456
	ds_read_b128 v[200:203], v159 offset:20480
	ds_read_b128 v[206:209], v159 offset:21504
	ds_read_b128 v[210:213], v159 offset:22528
	ds_read_b128 v[214:217], v159 offset:23552
	global_load_lds_dwordx4 v[218:219], off
	s_add_i32 m0, s12, 0x2000
	s_add_u32 s12, s80, 0x40000
	v_lshl_add_u64 v[220:221], s[80:81], 0, v[134:135]
	s_addc_u32 s13, s81, 0
	s_add_i32 s23, s95, s86
	global_load_lds_dwordx4 v[220:221], off
	v_lshl_add_u64 v[222:223], s[12:13], 0, v[130:131]
	s_mov_b32 m0, s23
	v_lshl_add_u64 v[224:225], s[82:83], 0, v[132:133]
	global_load_lds_dwordx4 v[222:223], off
	v_lshl_add_u64 v[222:223], s[12:13], 0, v[134:135]
	s_add_i32 m0, s23, 0x2000
	s_nop 0
	global_load_lds_dwordx4 v[222:223], off
	v_lshl_add_u64 v[222:223], s[82:83], 0, v[128:129]
	s_mov_b32 m0, s87
	s_nop 0
	global_load_lds_dwordx4 v[222:223], off
	s_mov_b32 m0, s88
	s_nop 0
	global_load_lds_dwordx4 v[224:225], off
	s_waitcnt vmcnt(8)
	s_waitcnt lgkmcnt(0)
	s_barrier
; #define PG8_STAGE(bufoff, gbase, voff) do { _Pragma("unroll") for (int _i = 0; _i < 2; ++_i) \
;         __builtin_amdgcn_global_load_lds((const unsigned*)((const char*)(gbase) + (voff)[_i]), (PG8_LAS unsigned*)(lds + (bufoff) + ldsw + _i * 8192), 16, 0, 0); } while (0)
; #define PG8_LDA(dst, b, h) do { _Pragma("unroll") for (int m = 0; m < 4; ++m) _Pragma("unroll") for (int k = 0; k < 2; ++k) dst[m][k] = *(const PG8_LAS bf16x8*)(lds + PG8_SA(b, h) + aoff + m * 2048 + k * 1024); } while (0)
; #define PG8_LDB(dst, b, h) do { _Pragma("unroll") for (int n = 0; n < 2; ++n) _Pragma("unroll") for (int k = 0; k < 2; ++k) dst[n][k] = *(const PG8_LAS bf16x8*)(lds + PG8_SB(b, h) + boff + n * 2048 + k * 1024); } while (0)
; #define PG8_MMA(ai, bj, At, Bt) do { __builtin_amdgcn_s_setprio(1); _Pragma("unroll") for (int m = 0; m < 4; ++m) _Pragma("unroll") for (int n = 0; n < 2; ++n) _Pragma("unroll") for (int k = 0; k < 2; ++k) \
;         acc[ai][bj][m][n] = __builtin_amdgcn_mfma_f32_16x16x32_bf16(Bt[n][k], At[m][k], acc[ai][bj][m][n], 0, 0, 0); __builtin_amdgcn_s_setprio(0); } while (0)
; #define PG8_WAIT_V(n) asm volatile("s_waitcnt vmcnt(" #n ")" ::: "memory")
; #define PG8_WAIT_L(n) asm volatile("s_waitcnt lgkmcnt(" #n ")" ::: "memory")
; #define PG8_BAR __builtin_amdgcn_s_barrier()
; #define PG8_SCHED __builtin_amdgcn_sched_barrier(0)
; template <class Epi, class Sched, bool ALIGN_EPI = false, bool SP2 = false>
; __device__ __forceinline__ void gemm_phase(PG8_LAS unsigned char* lds, const Gemm g, const Sched& S, const Epi& E) {
;     ...
;             PG8_WAIT_V(8); PG8_WAIT_L(0); PG8_BAR; PG8_MMA(1, 0, At, B0); PG8_MMA(1, 1, At, B1); PG8_BAR; PG8_SCHED;
;             PG8_LDB(B0, 1, 0); PG8_LDB(B1, 1, 1); PG8_SCHED; PG8_LDA(At, 1, 0); PG8_STAGE(PG8_SA(0, 1), a2 + hstep, voffA);
;             PG8_WAIT_V(8); PG8_WAIT_L(0); PG8_BAR; PG8_MMA(0, 0, At, B0); PG8_MMA(0, 1, At, B1); PG8_BAR; PG8_SCHED;
	s_setprio 1
	s_waitcnt lgkmcnt(0)
	v_mfma_f32_16x16x32_bf16 v[60:63], v[146:149], v[184:187], v[60:63]
	v_mfma_f32_16x16x32_bf16 v[56:59], v[160:163], v[184:187], v[56:59]
	v_mfma_f32_16x16x32_bf16 v[44:47], v[146:149], v[192:195], v[44:47]
	v_mfma_f32_16x16x32_bf16 v[40:43], v[160:163], v[192:195], v[40:43]
	v_mfma_f32_16x16x32_bf16 v[28:31], v[146:149], v[200:203], v[28:31]
	v_mfma_f32_16x16x32_bf16 v[24:27], v[160:163], v[200:203], v[24:27]
	v_mfma_f32_16x16x32_bf16 v[12:15], v[146:149], v[210:213], v[12:15]
	v_mfma_f32_16x16x32_bf16 v[8:11], v[160:163], v[210:213], v[8:11]
	v_mfma_f32_16x16x32_bf16 v[60:63], v[150:153], v[188:191], v[60:63]
	v_mfma_f32_16x16x32_bf16 v[56:59], v[164:167], v[188:191], v[56:59]
	v_mfma_f32_16x16x32_bf16 v[44:47], v[150:153], v[196:199], v[44:47]
	v_mfma_f32_16x16x32_bf16 v[40:43], v[164:167], v[196:199], v[40:43]
	v_mfma_f32_16x16x32_bf16 v[28:31], v[150:153], v[206:209], v[28:31]
	v_mfma_f32_16x16x32_bf16 v[24:27], v[164:167], v[206:209], v[24:27]
	v_mfma_f32_16x16x32_bf16 v[12:15], v[150:153], v[214:217], v[12:15]
	v_mfma_f32_16x16x32_bf16 v[8:11], v[164:167], v[214:217], v[8:11]
	v_mfma_f32_16x16x32_bf16 v[52:55], v[168:171], v[184:187], v[52:55]
	v_mfma_f32_16x16x32_bf16 v[48:51], v[176:179], v[184:187], v[48:51]
	v_mfma_f32_16x16x32_bf16 v[36:39], v[168:171], v[192:195], v[36:39]
	v_mfma_f32_16x16x32_bf16 v[32:35], v[176:179], v[192:195], v[32:35]
	v_mfma_f32_16x16x32_bf16 v[20:23], v[168:171], v[200:203], v[20:23]
	v_mfma_f32_16x16x32_bf16 v[16:19], v[176:179], v[200:203], v[16:19]
	v_mfma_f32_16x16x32_bf16 v[4:7], v[168:171], v[210:213], v[4:7]
	v_mfma_f32_16x16x32_bf16 v[0:3], v[176:179], v[210:213], v[0:3]
	v_mfma_f32_16x16x32_bf16 v[52:55], v[172:175], v[188:191], v[52:55]
	v_mfma_f32_16x16x32_bf16 v[48:51], v[180:183], v[188:191], v[48:51]
	v_mfma_f32_16x16x32_bf16 v[36:39], v[172:175], v[196:199], v[36:39]
	v_mfma_f32_16x16x32_bf16 v[32:35], v[180:183], v[196:199], v[32:35]
	v_mfma_f32_16x16x32_bf16 v[20:23], v[172:175], v[206:209], v[20:23]
	v_mfma_f32_16x16x32_bf16 v[16:19], v[180:183], v[206:209], v[16:19]
	v_mfma_f32_16x16x32_bf16 v[4:7], v[172:175], v[214:217], v[4:7]
	v_mfma_f32_16x16x32_bf16 v[0:3], v[180:183], v[214:217], v[0:3]
	s_setprio 0
	s_barrier
	s_add_i32 s23, 0, 0x18000
	v_add_u32_e32 v136, s23, v155
	s_add_i32 s25, 0, 0x1c000
	ds_read_b128 v[146:149], v136
	ds_read_b128 v[150:153], v136 offset:1024
	ds_read_b128 v[160:163], v136 offset:2048
	ds_read_b128 v[164:167], v136 offset:3072
	v_add_u32_e32 v136, s25, v155
	ds_read_b128 v[168:171], v136
	ds_read_b128 v[172:175], v136 offset:1024
	ds_read_b128 v[176:179], v136 offset:2048
	ds_read_b128 v[180:183], v136 offset:3072
	s_add_u32 s12, s82, 0x40000
	s_addc_u32 s13, s83, 0
	s_mov_b32 m0, s89
	v_lshl_add_u64 v[226:227], s[12:13], 0, v[128:129]
	ds_read_b128 v[184:187], v159 offset:32768
	ds_read_b128 v[188:191], v159 offset:33792
	ds_read_b128 v[192:195], v159 offset:34816
	ds_read_b128 v[196:199], v159 offset:35840
	ds_read_b128 v[200:203], v159 offset:36864
	ds_read_b128 v[206:209], v159 offset:37888
	ds_read_b128 v[210:213], v159 offset:38912
	ds_read_b128 v[214:217], v159 offset:39936
	global_load_lds_dwordx4 v[226:227], off
	v_lshl_add_u64 v[226:227], s[12:13], 0, v[132:133]
	s_mov_b32 m0, s90
	s_nop 0
	global_load_lds_dwordx4 v[226:227], off
	s_waitcnt vmcnt(8)
	s_waitcnt lgkmcnt(0)
	s_barrier
	s_setprio 1
	s_waitcnt lgkmcnt(0)
	v_mfma_f32_16x16x32_bf16 v[124:127], v[146:149], v[184:187], v[124:127]
	v_mfma_f32_16x16x32_bf16 v[120:123], v[160:163], v[184:187], v[120:123]
	v_mfma_f32_16x16x32_bf16 v[108:111], v[146:149], v[192:195], v[108:111]
	v_mfma_f32_16x16x32_bf16 v[104:107], v[160:163], v[192:195], v[104:107]
	v_mfma_f32_16x16x32_bf16 v[92:95], v[146:149], v[200:203], v[92:95]
	v_mfma_f32_16x16x32_bf16 v[88:91], v[160:163], v[200:203], v[88:91]
	v_mfma_f32_16x16x32_bf16 v[76:79], v[146:149], v[210:213], v[76:79]
	v_mfma_f32_16x16x32_bf16 v[72:75], v[160:163], v[210:213], v[72:75]
	v_mfma_f32_16x16x32_bf16 v[124:127], v[150:153], v[188:191], v[124:127]
	v_mfma_f32_16x16x32_bf16 v[120:123], v[164:167], v[188:191], v[120:123]
	v_mfma_f32_16x16x32_bf16 v[108:111], v[150:153], v[196:199], v[108:111]
	v_mfma_f32_16x16x32_bf16 v[104:107], v[164:167], v[196:199], v[104:107]
	v_mfma_f32_16x16x32_bf16 v[92:95], v[150:153], v[206:209], v[92:95]
	v_mfma_f32_16x16x32_bf16 v[88:91], v[164:167], v[206:209], v[88:91]
	v_mfma_f32_16x16x32_bf16 v[76:79], v[150:153], v[214:217], v[76:79]
	v_mfma_f32_16x16x32_bf16 v[72:75], v[164:167], v[214:217], v[72:75]
	v_mfma_f32_16x16x32_bf16 v[116:119], v[168:171], v[184:187], v[116:119]
	v_mfma_f32_16x16x32_bf16 v[112:115], v[176:179], v[184:187], v[112:115]
	v_mfma_f32_16x16x32_bf16 v[100:103], v[168:171], v[192:195], v[100:103]
	v_mfma_f32_16x16x32_bf16 v[96:99], v[176:179], v[192:195], v[96:99]
	v_mfma_f32_16x16x32_bf16 v[84:87], v[168:171], v[200:203], v[84:87]
	v_mfma_f32_16x16x32_bf16 v[80:83], v[176:179], v[200:203], v[80:83]
	v_mfma_f32_16x16x32_bf16 v[68:71], v[168:171], v[210:213], v[68:71]
	v_mfma_f32_16x16x32_bf16 v[64:67], v[176:179], v[210:213], v[64:67]
	v_mfma_f32_16x16x32_bf16 v[116:119], v[172:175], v[188:191], v[116:119]
	v_mfma_f32_16x16x32_bf16 v[112:115], v[180:183], v[188:191], v[112:115]
	v_mfma_f32_16x16x32_bf16 v[100:103], v[172:175], v[196:199], v[100:103]
	v_mfma_f32_16x16x32_bf16 v[96:99], v[180:183], v[196:199], v[96:99]
	v_mfma_f32_16x16x32_bf16 v[84:87], v[172:175], v[206:209], v[84:87]
	v_mfma_f32_16x16x32_bf16 v[80:83], v[180:183], v[206:209], v[80:83]
	v_mfma_f32_16x16x32_bf16 v[68:71], v[172:175], v[214:217], v[68:71]
	v_mfma_f32_16x16x32_bf16 v[64:67], v[180:183], v[214:217], v[64:67]
	s_setprio 0
	s_barrier
; #define PG8_STAGE(bufoff, gbase, voff) do { _Pragma("unroll") for (int _i = 0; _i < 2; ++_i) \
;         __builtin_amdgcn_global_load_lds((const unsigned*)((const char*)(gbase) + (voff)[_i]), (PG8_LAS unsigned*)(lds + (bufoff) + ldsw + _i * 8192), 16, 0, 0); } while (0)
; #define PG8_LDA(dst, b, h) do { _Pragma("unroll") for (int m = 0; m < 4; ++m) _Pragma("unroll") for (int k = 0; k < 2; ++k) dst[m][k] = *(const PG8_LAS bf16x8*)(lds + PG8_SA(b, h) + aoff + m * 2048 + k * 1024); } while (0)
; #define PG8_MMA(ai, bj, At, Bt) do { __builtin_amdgcn_s_setprio(1); _Pragma("unroll") for (int m = 0; m < 4; ++m) _Pragma("unroll") for (int n = 0; n < 2; ++n) _Pragma("unroll") for (int k = 0; k < 2; ++k) \
;         acc[ai][bj][m][n] = __builtin_amdgcn_mfma_f32_16x16x32_bf16(Bt[n][k], At[m][k], acc[ai][bj][m][n], 0, 0, 0); __builtin_amdgcn_s_setprio(0); } while (0)
; #define PG8_WAIT_V(n) asm volatile("s_waitcnt vmcnt(" #n ")" ::: "memory")
; #define PG8_WAIT_L(n) asm volatile("s_waitcnt lgkmcnt(" #n ")" ::: "memory")
; #define PG8_BAR __builtin_amdgcn_s_barrier()
; #define PG8_SCHED __builtin_amdgcn_sched_barrier(0)
; template <class Epi, class Sched, bool ALIGN_EPI = false, bool SP2 = false>
; __device__ __forceinline__ void gemm_phase(PG8_LAS unsigned char* lds, const Gemm g, const Sched& S, const Epi& E) {
;     ...
;             PG8_LDA(At, 1, 1); PG8_STAGE(PG8_SB(1, 0), b3, voffB); PG8_STAGE(PG8_SB(1, 1), b3 + hstep, voffB); PG8_STAGE(PG8_SA(1, 0), a3, voffA);
;             PG8_WAIT_V(8); PG8_WAIT_L(0); PG8_BAR; PG8_MMA(1, 0, At, B0); PG8_MMA(1, 1, At, B1); PG8_BAR; PG8_SCHED;
	s_add_i32 s12, s23, s86
	v_lshl_add_u64 v[218:219], v[218:219], 0, s[18:19]
	s_mov_b32 m0, s12
	ds_read_b128 v[184:187], v159 offset:49152
	ds_read_b128 v[188:191], v159 offset:50176
	ds_read_b128 v[192:195], v159 offset:51200
	ds_read_b128 v[196:199], v159 offset:52224
	ds_read_b128 v[200:203], v159 offset:53248
	ds_read_b128 v[206:209], v159 offset:54272
	ds_read_b128 v[210:213], v159 offset:55296
	ds_read_b128 v[214:217], v159 offset:56320
	global_load_lds_dwordx4 v[218:219], off
	s_add_i32 m0, s12, 0x2000
	s_add_u32 s12, s80, 0x40080
	v_lshl_add_u64 v[218:219], v[220:221], 0, s[18:19]
	s_addc_u32 s13, s81, 0
	s_add_i32 s23, s25, s86
	global_load_lds_dwordx4 v[218:219], off
	v_lshl_add_u64 v[218:219], s[12:13], 0, v[130:131]
	s_mov_b32 m0, s23
	s_nop 0
	global_load_lds_dwordx4 v[218:219], off
	v_lshl_add_u64 v[218:219], s[12:13], 0, v[134:135]
	s_add_i32 m0, s23, 0x2000
	s_nop 0
	global_load_lds_dwordx4 v[218:219], off
	v_lshl_add_u64 v[218:219], v[222:223], 0, s[18:19]
	s_mov_b32 m0, s92
	s_nop 0
	global_load_lds_dwordx4 v[218:219], off
	v_lshl_add_u64 v[218:219], v[224:225], 0, s[18:19]
	s_mov_b32 m0, s93
	s_nop 0
	global_load_lds_dwordx4 v[218:219], off
	s_waitcnt vmcnt(8)
	s_waitcnt lgkmcnt(0)
	s_barrier
	s_setprio 1
	s_waitcnt lgkmcnt(0)
	v_mfma_f32_16x16x32_bf16 v[60:63], v[146:149], v[184:187], v[60:63]
	v_mfma_f32_16x16x32_bf16 v[56:59], v[160:163], v[184:187], v[56:59]
	v_mfma_f32_16x16x32_bf16 v[44:47], v[146:149], v[192:195], v[44:47]
	v_mfma_f32_16x16x32_bf16 v[40:43], v[160:163], v[192:195], v[40:43]
	v_mfma_f32_16x16x32_bf16 v[28:31], v[146:149], v[200:203], v[28:31]
	v_mfma_f32_16x16x32_bf16 v[24:27], v[160:163], v[200:203], v[24:27]
	v_mfma_f32_16x16x32_bf16 v[12:15], v[146:149], v[210:213], v[12:15]
	v_mfma_f32_16x16x32_bf16 v[8:11], v[160:163], v[210:213], v[8:11]
	v_mfma_f32_16x16x32_bf16 v[60:63], v[150:153], v[188:191], v[60:63]
	v_mfma_f32_16x16x32_bf16 v[56:59], v[164:167], v[188:191], v[56:59]
	v_mfma_f32_16x16x32_bf16 v[44:47], v[150:153], v[196:199], v[44:47]
	v_mfma_f32_16x16x32_bf16 v[40:43], v[164:167], v[196:199], v[40:43]
	v_mfma_f32_16x16x32_bf16 v[28:31], v[150:153], v[206:209], v[28:31]
	v_mfma_f32_16x16x32_bf16 v[24:27], v[164:167], v[206:209], v[24:27]
	v_mfma_f32_16x16x32_bf16 v[12:15], v[150:153], v[214:217], v[12:15]
	v_mfma_f32_16x16x32_bf16 v[8:11], v[164:167], v[214:217], v[8:11]
	v_mfma_f32_16x16x32_bf16 v[52:55], v[168:171], v[184:187], v[52:55]
	v_mfma_f32_16x16x32_bf16 v[48:51], v[176:179], v[184:187], v[48:51]
	v_mfma_f32_16x16x32_bf16 v[36:39], v[168:171], v[192:195], v[36:39]
	v_mfma_f32_16x16x32_bf16 v[32:35], v[176:179], v[192:195], v[32:35]
	v_mfma_f32_16x16x32_bf16 v[20:23], v[168:171], v[200:203], v[20:23]
	v_mfma_f32_16x16x32_bf16 v[16:19], v[176:179], v[200:203], v[16:19]
	v_mfma_f32_16x16x32_bf16 v[4:7], v[168:171], v[210:213], v[4:7]
	v_mfma_f32_16x16x32_bf16 v[0:3], v[176:179], v[210:213], v[0:3]
	v_mfma_f32_16x16x32_bf16 v[52:55], v[172:175], v[188:191], v[52:55]
	v_mfma_f32_16x16x32_bf16 v[48:51], v[180:183], v[188:191], v[48:51]
	v_mfma_f32_16x16x32_bf16 v[36:39], v[172:175], v[196:199], v[36:39]
	v_mfma_f32_16x16x32_bf16 v[32:35], v[180:183], v[196:199], v[32:35]
	v_mfma_f32_16x16x32_bf16 v[20:23], v[172:175], v[206:209], v[20:23]
	v_mfma_f32_16x16x32_bf16 v[16:19], v[180:183], v[206:209], v[16:19]
	v_mfma_f32_16x16x32_bf16 v[4:7], v[172:175], v[214:217], v[4:7]
	v_mfma_f32_16x16x32_bf16 v[0:3], v[180:183], v[214:217], v[0:3]
	s_setprio 0
	s_barrier
	s_add_i32 s11, s11, 2
	s_add_u32 s78, s78, 0x100
	s_addc_u32 s79, s79, 0
	s_add_u32 s9, s9, 0x100
	s_addc_u32 s10, s10, 0
	s_cmp_gt_u32 s11, 13
	s_cbranch_scc0 .LBB0_124
	s_and_b64 vcc, exec, s[20:21]
	s_cbranch_vccz .LBB0_127
	s_barrier

; #define PG8_STAGE(bufoff, gbase, voff) do { _Pragma("unroll") for (int _i = 0; _i < 2; ++_i) \
;         __builtin_amdgcn_global_load_lds((const unsigned*)((const char*)(gbase) + (voff)[_i]), (PG8_LAS unsigned*)(lds + (bufoff) + ldsw + _i * 8192), 16, 0, 0); } while (0)
; #define PG8_LDA(dst, b, h) do { _Pragma("unroll") for (int m = 0; m < 4; ++m) _Pragma("unroll") for (int k = 0; k < 2; ++k) dst[m][k] = *(const PG8_LAS bf16x8*)(lds + PG8_SA(b, h) + aoff + m * 2048 + k * 1024); } while (0)
; #define PG8_LDB(dst, b, h) do { _Pragma("unroll") for (int n = 0; n < 2; ++n) _Pragma("unroll") for (int k = 0; k < 2; ++k) dst[n][k] = *(const PG8_LAS bf16x8*)(lds + PG8_SB(b, h) + boff + n * 2048 + k * 1024); } while (0)
; #define PG8_MMA(ai, bj, At, Bt) do { __builtin_amdgcn_s_setprio(1); _Pragma("unroll") for (int m = 0; m < 4; ++m) _Pragma("unroll") for (int n = 0; n < 2; ++n) _Pragma("unroll") for (int k = 0; k < 2; ++k) \
;         acc[ai][bj][m][n] = __builtin_amdgcn_mfma_f32_16x16x32_bf16(Bt[n][k], At[m][k], acc[ai][bj][m][n], 0, 0, 0); __builtin_amdgcn_s_setprio(0); } while (0)
; #define PG8_WAIT_V(n) asm volatile("s_waitcnt vmcnt(" #n ")" ::: "memory")
; #define PG8_WAIT_L(n) asm volatile("s_waitcnt lgkmcnt(" #n ")" ::: "memory")
; #define PG8_BAR __builtin_amdgcn_s_barrier()
; #define PG8_SCHED __builtin_amdgcn_sched_barrier(0)
; template <class Epi, class Sched, bool ALIGN_EPI = false, bool SP2 = false>
; __device__ __forceinline__ void gemm_phase(PG8_LAS unsigned char* lds, const Gemm g, const Sched& S, const Epi& E) {
;     ...
;             const bool last = (t == nt - 2);
;             const char* a1 = cA + (size_t)(t + 1) * kstep;
;             const char* a2 = last ? nA : cA + (size_t)(t + 2) * kstep; const char* b2 = last ? nB : cB + (size_t)(t + 2) * kstep;
;             const char* a3 = a2 + kstep; const char* b3 = b2 + kstep;
;             if (last && has_next) S.a_ready(nxt);
;             if constexpr (SP2) {
;             PG8_LDB(B0, 0, 0); PG8_LDB(B1, 0, 1); PG8_SCHED; PG8_LDA(At, 0, 0); PG8_STAGE(PG8_SA(1, 1), a1 + hstep, voffA);
;             PG8_WAIT_V(8); PG8_WAIT_L(0); PG8_BAR; PG8_MMA(0, 0, At, B0); PG8_MMA(0, 1, At, B1); PG8_BAR; PG8_SCHED;
;             PG8_LDA(At, 0, 1); PG8_STAGE(PG8_SB(0, 0), b2, voffB); PG8_STAGE(PG8_SB(0, 1), b2 + hstep, voffB); PG8_STAGE(PG8_SA(0, 0), a2, voffA);
.LBB0_563:
	ds_read_b128 v[128:131], v157
	ds_read_b128 v[148:151], v157 offset:1024
	ds_read_b128 v[160:163], v157 offset:2048
	ds_read_b128 v[164:167], v157 offset:3072
	ds_read_b128 v[168:171], v158
	ds_read_b128 v[172:175], v158 offset:1024
	ds_read_b128 v[176:179], v158 offset:2048
	ds_read_b128 v[180:183], v158 offset:3072
	s_add_u32 s48, s46, 0xfffc0080
	s_addc_u32 s49, s47, -1
	s_cmp_eq_u32 s62, 12
	s_cselect_b32 s55, s39, s49
	s_cselect_b32 s54, s58, s48
	s_cselect_b32 s49, s27, s61
	s_cselect_b32 s48, s59, s60
	v_lshl_add_u64 v[218:219], s[46:47], 0, v[140:141]
	s_add_i32 m0, s3, 0xc000
	ds_read_b128 v[184:187], v159
	ds_read_b128 v[188:191], v159 offset:1024
	ds_read_b128 v[192:195], v159 offset:2048
	ds_read_b128 v[196:199], v159 offset:3072
	ds_read_b128 v[200:203], v159 offset:4096
	ds_read_b128 v[206:209], v159 offset:5120
	ds_read_b128 v[210:213], v159 offset:6144
	ds_read_b128 v[214:217], v159 offset:7168
	global_load_lds_dwordx4 v[218:219], off
	v_lshl_add_u64 v[218:219], s[46:47], 0, v[142:143]
	s_add_i32 m0, s3, 0xe000
	s_nop 0
	global_load_lds_dwordx4 v[218:219], off
	s_waitcnt vmcnt(8)
	s_waitcnt lgkmcnt(0)
	s_barrier
	s_setprio 1
	s_waitcnt lgkmcnt(0)
	v_mfma_f32_16x16x32_bf16 v[124:127], v[128:131], v[184:187], v[124:127]
	v_mfma_f32_16x16x32_bf16 v[120:123], v[160:163], v[184:187], v[120:123]
	v_mfma_f32_16x16x32_bf16 v[116:119], v[128:131], v[192:195], v[116:119]
	v_mfma_f32_16x16x32_bf16 v[108:111], v[160:163], v[192:195], v[108:111]
	v_mfma_f32_16x16x32_bf16 v[100:103], v[128:131], v[200:203], v[100:103]
	v_mfma_f32_16x16x32_bf16 v[92:95], v[160:163], v[200:203], v[92:95]
	v_mfma_f32_16x16x32_bf16 v[84:87], v[128:131], v[210:213], v[84:87]
	v_mfma_f32_16x16x32_bf16 v[76:79], v[160:163], v[210:213], v[76:79]
	v_mfma_f32_16x16x32_bf16 v[124:127], v[148:151], v[188:191], v[124:127]
	v_mfma_f32_16x16x32_bf16 v[120:123], v[164:167], v[188:191], v[120:123]
	v_mfma_f32_16x16x32_bf16 v[116:119], v[148:151], v[196:199], v[116:119]
	v_mfma_f32_16x16x32_bf16 v[108:111], v[164:167], v[196:199], v[108:111]
	v_mfma_f32_16x16x32_bf16 v[100:103], v[148:151], v[206:209], v[100:103]
	v_mfma_f32_16x16x32_bf16 v[92:95], v[164:167], v[206:209], v[92:95]
	v_mfma_f32_16x16x32_bf16 v[84:87], v[148:151], v[214:217], v[84:87]
	v_mfma_f32_16x16x32_bf16 v[76:79], v[164:167], v[214:217], v[76:79]
	v_mfma_f32_16x16x32_bf16 v[112:115], v[168:171], v[184:187], v[112:115]
	v_mfma_f32_16x16x32_bf16 v[104:107], v[176:179], v[184:187], v[104:107]
	v_mfma_f32_16x16x32_bf16 v[96:99], v[168:171], v[192:195], v[96:99]
	v_mfma_f32_16x16x32_bf16 v[88:91], v[176:179], v[192:195], v[88:91]
	v_mfma_f32_16x16x32_bf16 v[80:83], v[168:171], v[200:203], v[80:83]
	v_mfma_f32_16x16x32_bf16 v[72:75], v[176:179], v[200:203], v[72:75]
	v_mfma_f32_16x16x32_bf16 v[68:71], v[168:171], v[210:213], v[68:71]
	v_mfma_f32_16x16x32_bf16 v[64:67], v[176:179], v[210:213], v[64:67]
	v_mfma_f32_16x16x32_bf16 v[112:115], v[172:175], v[188:191], v[112:115]
	v_mfma_f32_16x16x32_bf16 v[104:107], v[180:183], v[188:191], v[104:107]
	v_mfma_f32_16x16x32_bf16 v[96:99], v[172:175], v[196:199], v[96:99]
	v_mfma_f32_16x16x32_bf16 v[88:91], v[180:183], v[196:199], v[88:91]
	v_mfma_f32_16x16x32_bf16 v[80:83], v[172:175], v[206:209], v[80:83]
	v_mfma_f32_16x16x32_bf16 v[72:75], v[180:183], v[206:209], v[72:75]
	v_mfma_f32_16x16x32_bf16 v[68:71], v[172:175], v[214:217], v[68:71]
	v_mfma_f32_16x16x32_bf16 v[64:67], v[180:183], v[214:217], v[64:67]
	s_setprio 0
	s_barrier
	s_add_i32 s63, s56, s28
	v_lshl_add_u64 v[218:219], s[48:49], 0, v[134:135]
	s_mov_b32 m0, s63
	ds_read_b128 v[184:187], v159 offset:16384
	ds_read_b128 v[188:191], v159 offset:17408
	ds_read_b128 v[192:195], v159 offset:18432
	ds_read_b128 v[196:199], v159 offset:19456
	ds_read_b128 v[200:203], v159 offset:20480
	ds_read_b128 v[206:209], v159 offset:21504
	ds_read_b128 v[210:213], v159 offset:22528
	ds_read_b128 v[214:217], v159 offset:23552
	global_load_lds_dwordx4 v[218:219], off
	s_add_i32 m0, s63, 0x2000
	s_add_u32 s64, s48, 0x40000
	v_lshl_add_u64 v[220:221], s[48:49], 0, v[138:139]
	s_addc_u32 s65, s49, 0
	s_add_i32 s63, s57, s28
	global_load_lds_dwordx4 v[220:221], off
	v_lshl_add_u64 v[222:223], s[64:65], 0, v[134:135]
	s_mov_b32 m0, s63
	v_lshl_add_u64 v[224:225], s[54:55], 0, v[136:137]
	global_load_lds_dwordx4 v[222:223], off
	v_lshl_add_u64 v[222:223], s[64:65], 0, v[138:139]
	s_add_i32 m0, s63, 0x2000
	s_nop 0
	global_load_lds_dwordx4 v[222:223], off
	v_lshl_add_u64 v[222:223], s[54:55], 0, v[132:133]
	s_mov_b32 m0, s3
	s_nop 0
	global_load_lds_dwordx4 v[222:223], off
	s_mov_b32 m0, s29
	s_nop 0
	global_load_lds_dwordx4 v[224:225], off
	s_waitcnt vmcnt(8)
	s_waitcnt lgkmcnt(0)
	s_barrier
; #define PG8_STAGE(bufoff, gbase, voff) do { _Pragma("unroll") for (int _i = 0; _i < 2; ++_i) \
;         __builtin_amdgcn_global_load_lds((const unsigned*)((const char*)(gbase) + (voff)[_i]), (PG8_LAS unsigned*)(lds + (bufoff) + ldsw + _i * 8192), 16, 0, 0); } while (0)
; #define PG8_LDA(dst, b, h) do { _Pragma("unroll") for (int m = 0; m < 4; ++m) _Pragma("unroll") for (int k = 0; k < 2; ++k) dst[m][k] = *(const PG8_LAS bf16x8*)(lds + PG8_SA(b, h) + aoff + m * 2048 + k * 1024); } while (0)
; #define PG8_LDB(dst, b, h) do { _Pragma("unroll") for (int n = 0; n < 2; ++n) _Pragma("unroll") for (int k = 0; k < 2; ++k) dst[n][k] = *(const PG8_LAS bf16x8*)(lds + PG8_SB(b, h) + boff + n * 2048 + k * 1024); } while (0)
; #define PG8_MMA(ai, bj, At, Bt) do { __builtin_amdgcn_s_setprio(1); _Pragma("unroll") for (int m = 0; m < 4; ++m) _Pragma("unroll") for (int n = 0; n < 2; ++n) _Pragma("unroll") for (int k = 0; k < 2; ++k) \
;         acc[ai][bj][m][n] = __builtin_amdgcn_mfma_f32_16x16x32_bf16(Bt[n][k], At[m][k], acc[ai][bj][m][n], 0, 0, 0); __builtin_amdgcn_s_setprio(0); } while (0)
; #define PG8_WAIT_V(n) asm volatile("s_waitcnt vmcnt(" #n ")" ::: "memory")
; #define PG8_WAIT_L(n) asm volatile("s_waitcnt lgkmcnt(" #n ")" ::: "memory")
; #define PG8_BAR __builtin_amdgcn_s_barrier()
; #define PG8_SCHED __builtin_amdgcn_sched_barrier(0)
; template <class Epi, class Sched, bool ALIGN_EPI = false, bool SP2 = false>
; __device__ __forceinline__ void gemm_phase(PG8_LAS unsigned char* lds, const Gemm g, const Sched& S, const Epi& E) {
;     ...
;             PG8_WAIT_V(8); PG8_WAIT_L(0); PG8_BAR; PG8_MMA(1, 0, At, B0); PG8_MMA(1, 1, At, B1); PG8_BAR; PG8_SCHED;
;             PG8_LDB(B0, 1, 0); PG8_LDB(B1, 1, 1); PG8_SCHED; PG8_LDA(At, 1, 0); PG8_STAGE(PG8_SA(0, 1), a2 + hstep, voffA);
;             PG8_WAIT_V(8); PG8_WAIT_L(0); PG8_BAR; PG8_MMA(0, 0, At, B0); PG8_MMA(0, 1, At, B1); PG8_BAR; PG8_SCHED;
	s_setprio 1
	s_waitcnt lgkmcnt(0)
	v_mfma_f32_16x16x32_bf16 v[60:63], v[128:131], v[184:187], v[60:63]
	v_mfma_f32_16x16x32_bf16 v[56:59], v[160:163], v[184:187], v[56:59]
	v_mfma_f32_16x16x32_bf16 v[52:55], v[128:131], v[192:195], v[52:55]
	v_mfma_f32_16x16x32_bf16 v[44:47], v[160:163], v[192:195], v[44:47]
	v_mfma_f32_16x16x32_bf16 v[36:39], v[128:131], v[200:203], v[36:39]
	v_mfma_f32_16x16x32_bf16 v[28:31], v[160:163], v[200:203], v[28:31]
	v_mfma_f32_16x16x32_bf16 v[20:23], v[128:131], v[210:213], v[20:23]
	v_mfma_f32_16x16x32_bf16 v[12:15], v[160:163], v[210:213], v[12:15]
	v_mfma_f32_16x16x32_bf16 v[60:63], v[148:151], v[188:191], v[60:63]
	v_mfma_f32_16x16x32_bf16 v[56:59], v[164:167], v[188:191], v[56:59]
	v_mfma_f32_16x16x32_bf16 v[52:55], v[148:151], v[196:199], v[52:55]
	v_mfma_f32_16x16x32_bf16 v[44:47], v[164:167], v[196:199], v[44:47]
	v_mfma_f32_16x16x32_bf16 v[36:39], v[148:151], v[206:209], v[36:39]
	v_mfma_f32_16x16x32_bf16 v[28:31], v[164:167], v[206:209], v[28:31]
	v_mfma_f32_16x16x32_bf16 v[20:23], v[148:151], v[214:217], v[20:23]
	v_mfma_f32_16x16x32_bf16 v[12:15], v[164:167], v[214:217], v[12:15]
	v_mfma_f32_16x16x32_bf16 v[48:51], v[168:171], v[184:187], v[48:51]
	v_mfma_f32_16x16x32_bf16 v[40:43], v[176:179], v[184:187], v[40:43]
	v_mfma_f32_16x16x32_bf16 v[32:35], v[168:171], v[192:195], v[32:35]
	v_mfma_f32_16x16x32_bf16 v[24:27], v[176:179], v[192:195], v[24:27]
	v_mfma_f32_16x16x32_bf16 v[16:19], v[168:171], v[200:203], v[16:19]
	v_mfma_f32_16x16x32_bf16 v[8:11], v[176:179], v[200:203], v[8:11]
	v_mfma_f32_16x16x32_bf16 v[4:7], v[168:171], v[210:213], v[4:7]
	v_mfma_f32_16x16x32_bf16 v[0:3], v[176:179], v[210:213], v[0:3]
	v_mfma_f32_16x16x32_bf16 v[48:51], v[172:175], v[188:191], v[48:51]
	v_mfma_f32_16x16x32_bf16 v[40:43], v[180:183], v[188:191], v[40:43]
	v_mfma_f32_16x16x32_bf16 v[32:35], v[172:175], v[196:199], v[32:35]
	v_mfma_f32_16x16x32_bf16 v[24:27], v[180:183], v[196:199], v[24:27]
	v_mfma_f32_16x16x32_bf16 v[16:19], v[172:175], v[206:209], v[16:19]
	v_mfma_f32_16x16x32_bf16 v[8:11], v[180:183], v[206:209], v[8:11]
	v_mfma_f32_16x16x32_bf16 v[4:7], v[172:175], v[214:217], v[4:7]
	v_mfma_f32_16x16x32_bf16 v[0:3], v[180:183], v[214:217], v[0:3]
	s_setprio 0
	s_barrier
	s_add_i32 s63, 0, 0x18000
	s_add_i32 s64, 0, 0x1c000
	v_add_u32_e32 v164, s63, v153
	v_add_u32_e32 v180, s64, v153
	ds_read_b128 v[128:131], v164
	ds_read_b128 v[148:151], v164 offset:1024
	ds_read_b128 v[160:163], v164 offset:2048
	ds_read_b128 v[164:167], v164 offset:3072
	ds_read_b128 v[168:171], v180
	ds_read_b128 v[172:175], v180 offset:1024
	ds_read_b128 v[176:179], v180 offset:2048
	ds_read_b128 v[180:183], v180 offset:3072
	s_add_u32 s54, s54, 0x40000
	s_addc_u32 s55, s55, 0
	s_mov_b32 m0, s30
	v_lshl_add_u64 v[226:227], s[54:55], 0, v[132:133]
	ds_read_b128 v[184:187], v159 offset:32768
	ds_read_b128 v[188:191], v159 offset:33792
	ds_read_b128 v[192:195], v159 offset:34816
	ds_read_b128 v[196:199], v159 offset:35840
	ds_read_b128 v[200:203], v159 offset:36864
	ds_read_b128 v[206:209], v159 offset:37888
	ds_read_b128 v[210:213], v159 offset:38912
	ds_read_b128 v[214:217], v159 offset:39936
	global_load_lds_dwordx4 v[226:227], off
	v_lshl_add_u64 v[226:227], s[54:55], 0, v[136:137]
	s_mov_b32 m0, s31
	s_nop 0
	global_load_lds_dwordx4 v[226:227], off
	s_waitcnt vmcnt(8)
	s_waitcnt lgkmcnt(0)
	s_barrier
	s_setprio 1
	s_waitcnt lgkmcnt(0)
	v_mfma_f32_16x16x32_bf16 v[124:127], v[128:131], v[184:187], v[124:127]
	v_mfma_f32_16x16x32_bf16 v[120:123], v[160:163], v[184:187], v[120:123]
	v_mfma_f32_16x16x32_bf16 v[116:119], v[128:131], v[192:195], v[116:119]
	v_mfma_f32_16x16x32_bf16 v[108:111], v[160:163], v[192:195], v[108:111]
	v_mfma_f32_16x16x32_bf16 v[100:103], v[128:131], v[200:203], v[100:103]
	v_mfma_f32_16x16x32_bf16 v[92:95], v[160:163], v[200:203], v[92:95]
	v_mfma_f32_16x16x32_bf16 v[84:87], v[128:131], v[210:213], v[84:87]
	v_mfma_f32_16x16x32_bf16 v[76:79], v[160:163], v[210:213], v[76:79]
	v_mfma_f32_16x16x32_bf16 v[124:127], v[148:151], v[188:191], v[124:127]
	v_mfma_f32_16x16x32_bf16 v[120:123], v[164:167], v[188:191], v[120:123]
	v_mfma_f32_16x16x32_bf16 v[116:119], v[148:151], v[196:199], v[116:119]
	v_mfma_f32_16x16x32_bf16 v[108:111], v[164:167], v[196:199], v[108:111]
	v_mfma_f32_16x16x32_bf16 v[100:103], v[148:151], v[206:209], v[100:103]
	v_mfma_f32_16x16x32_bf16 v[92:95], v[164:167], v[206:209], v[92:95]
	v_mfma_f32_16x16x32_bf16 v[84:87], v[148:151], v[214:217], v[84:87]
	v_mfma_f32_16x16x32_bf16 v[76:79], v[164:167], v[214:217], v[76:79]
	v_mfma_f32_16x16x32_bf16 v[112:115], v[168:171], v[184:187], v[112:115]
	v_mfma_f32_16x16x32_bf16 v[104:107], v[176:179], v[184:187], v[104:107]
	v_mfma_f32_16x16x32_bf16 v[96:99], v[168:171], v[192:195], v[96:99]
	v_mfma_f32_16x16x32_bf16 v[88:91], v[176:179], v[192:195], v[88:91]
	v_mfma_f32_16x16x32_bf16 v[80:83], v[168:171], v[200:203], v[80:83]
	v_mfma_f32_16x16x32_bf16 v[72:75], v[176:179], v[200:203], v[72:75]
	v_mfma_f32_16x16x32_bf16 v[68:71], v[168:171], v[210:213], v[68:71]
	v_mfma_f32_16x16x32_bf16 v[64:67], v[176:179], v[210:213], v[64:67]
	v_mfma_f32_16x16x32_bf16 v[112:115], v[172:175], v[188:191], v[112:115]
	v_mfma_f32_16x16x32_bf16 v[104:107], v[180:183], v[188:191], v[104:107]
	v_mfma_f32_16x16x32_bf16 v[96:99], v[172:175], v[196:199], v[96:99]
	v_mfma_f32_16x16x32_bf16 v[88:91], v[180:183], v[196:199], v[88:91]
	v_mfma_f32_16x16x32_bf16 v[80:83], v[172:175], v[206:209], v[80:83]
	v_mfma_f32_16x16x32_bf16 v[72:75], v[180:183], v[206:209], v[72:75]
	v_mfma_f32_16x16x32_bf16 v[68:71], v[172:175], v[214:217], v[68:71]
	v_mfma_f32_16x16x32_bf16 v[64:67], v[180:183], v[214:217], v[64:67]
	s_setprio 0
	s_barrier
; #define PG8_STAGE(bufoff, gbase, voff) do { _Pragma("unroll") for (int _i = 0; _i < 2; ++_i) \
;         __builtin_amdgcn_global_load_lds((const unsigned*)((const char*)(gbase) + (voff)[_i]), (PG8_LAS unsigned*)(lds + (bufoff) + ldsw + _i * 8192), 16, 0, 0); } while (0)
; #define PG8_LDA(dst, b, h) do { _Pragma("unroll") for (int m = 0; m < 4; ++m) _Pragma("unroll") for (int k = 0; k < 2; ++k) dst[m][k] = *(const PG8_LAS bf16x8*)(lds + PG8_SA(b, h) + aoff + m * 2048 + k * 1024); } while (0)
; #define PG8_MMA(ai, bj, At, Bt) do { __builtin_amdgcn_s_setprio(1); _Pragma("unroll") for (int m = 0; m < 4; ++m) _Pragma("unroll") for (int n = 0; n < 2; ++n) _Pragma("unroll") for (int k = 0; k < 2; ++k) \
;         acc[ai][bj][m][n] = __builtin_amdgcn_mfma_f32_16x16x32_bf16(Bt[n][k], At[m][k], acc[ai][bj][m][n], 0, 0, 0); __builtin_amdgcn_s_setprio(0); } while (0)
; #define PG8_WAIT_V(n) asm volatile("s_waitcnt vmcnt(" #n ")" ::: "memory")
; #define PG8_WAIT_L(n) asm volatile("s_waitcnt lgkmcnt(" #n ")" ::: "memory")
; #define PG8_BAR __builtin_amdgcn_s_barrier()
; #define PG8_SCHED __builtin_amdgcn_sched_barrier(0)
; template <class Epi, class Sched, bool ALIGN_EPI = false, bool SP2 = false>
; __device__ __forceinline__ void gemm_phase(PG8_LAS unsigned char* lds, const Gemm g, const Sched& S, const Epi& E) {
;     ...
;             PG8_LDA(At, 1, 1); PG8_STAGE(PG8_SB(1, 0), b3, voffB); PG8_STAGE(PG8_SB(1, 1), b3 + hstep, voffB); PG8_STAGE(PG8_SA(1, 0), a3, voffA);
;             PG8_WAIT_V(8); PG8_WAIT_L(0); PG8_BAR; PG8_MMA(1, 0, At, B0); PG8_MMA(1, 1, At, B1); PG8_BAR; PG8_SCHED;
	s_add_i32 s54, s63, s28
	v_lshl_add_u64 v[218:219], v[218:219], 0, s[16:17]
	s_mov_b32 m0, s54
	ds_read_b128 v[184:187], v159 offset:49152
	ds_read_b128 v[188:191], v159 offset:50176
	ds_read_b128 v[192:195], v159 offset:51200
	ds_read_b128 v[196:199], v159 offset:52224
	ds_read_b128 v[200:203], v159 offset:53248
	ds_read_b128 v[206:209], v159 offset:54272
	ds_read_b128 v[210:213], v159 offset:55296
	ds_read_b128 v[214:217], v159 offset:56320
	global_load_lds_dwordx4 v[218:219], off
	s_add_i32 m0, s54, 0x2000
	s_add_u32 s48, s48, 0x40080
	v_lshl_add_u64 v[218:219], v[220:221], 0, s[16:17]
	s_addc_u32 s49, s49, 0
	s_add_i32 s54, s64, s28
	global_load_lds_dwordx4 v[218:219], off
	v_lshl_add_u64 v[218:219], s[48:49], 0, v[134:135]
	s_mov_b32 m0, s54
	s_nop 0
	global_load_lds_dwordx4 v[218:219], off
	v_lshl_add_u64 v[218:219], s[48:49], 0, v[138:139]
	s_add_i32 m0, s54, 0x2000
	s_nop 0
	global_load_lds_dwordx4 v[218:219], off
	v_lshl_add_u64 v[218:219], v[222:223], 0, s[16:17]
	s_mov_b32 m0, s34
	s_nop 0
	global_load_lds_dwordx4 v[218:219], off
	v_lshl_add_u64 v[218:219], v[224:225], 0, s[16:17]
	s_mov_b32 m0, s35
	s_nop 0
	global_load_lds_dwordx4 v[218:219], off
	s_waitcnt vmcnt(8)
	s_waitcnt lgkmcnt(0)
	s_barrier
	s_setprio 1
	s_waitcnt lgkmcnt(0)
	v_mfma_f32_16x16x32_bf16 v[60:63], v[128:131], v[184:187], v[60:63]
	v_mfma_f32_16x16x32_bf16 v[56:59], v[160:163], v[184:187], v[56:59]
	v_mfma_f32_16x16x32_bf16 v[52:55], v[128:131], v[192:195], v[52:55]
	v_mfma_f32_16x16x32_bf16 v[44:47], v[160:163], v[192:195], v[44:47]
	v_mfma_f32_16x16x32_bf16 v[36:39], v[128:131], v[200:203], v[36:39]
	v_mfma_f32_16x16x32_bf16 v[28:31], v[160:163], v[200:203], v[28:31]
	v_mfma_f32_16x16x32_bf16 v[20:23], v[128:131], v[210:213], v[20:23]
	v_mfma_f32_16x16x32_bf16 v[12:15], v[160:163], v[210:213], v[12:15]
	v_mfma_f32_16x16x32_bf16 v[60:63], v[148:151], v[188:191], v[60:63]
	v_mfma_f32_16x16x32_bf16 v[56:59], v[164:167], v[188:191], v[56:59]
	v_mfma_f32_16x16x32_bf16 v[52:55], v[148:151], v[196:199], v[52:55]
	v_mfma_f32_16x16x32_bf16 v[44:47], v[164:167], v[196:199], v[44:47]
	v_mfma_f32_16x16x32_bf16 v[36:39], v[148:151], v[206:209], v[36:39]
	v_mfma_f32_16x16x32_bf16 v[28:31], v[164:167], v[206:209], v[28:31]
	v_mfma_f32_16x16x32_bf16 v[20:23], v[148:151], v[214:217], v[20:23]
	v_mfma_f32_16x16x32_bf16 v[12:15], v[164:167], v[214:217], v[12:15]
	v_mfma_f32_16x16x32_bf16 v[48:51], v[168:171], v[184:187], v[48:51]
	v_mfma_f32_16x16x32_bf16 v[40:43], v[176:179], v[184:187], v[40:43]
	v_mfma_f32_16x16x32_bf16 v[32:35], v[168:171], v[192:195], v[32:35]
	v_mfma_f32_16x16x32_bf16 v[24:27], v[176:179], v[192:195], v[24:27]
	v_mfma_f32_16x16x32_bf16 v[16:19], v[168:171], v[200:203], v[16:19]
	v_mfma_f32_16x16x32_bf16 v[8:11], v[176:179], v[200:203], v[8:11]
	v_mfma_f32_16x16x32_bf16 v[4:7], v[168:171], v[210:213], v[4:7]
	v_mfma_f32_16x16x32_bf16 v[0:3], v[176:179], v[210:213], v[0:3]
	v_mfma_f32_16x16x32_bf16 v[48:51], v[172:175], v[188:191], v[48:51]
	v_mfma_f32_16x16x32_bf16 v[40:43], v[180:183], v[188:191], v[40:43]
	v_mfma_f32_16x16x32_bf16 v[32:35], v[172:175], v[196:199], v[32:35]
	v_mfma_f32_16x16x32_bf16 v[24:27], v[180:183], v[196:199], v[24:27]
	v_mfma_f32_16x16x32_bf16 v[16:19], v[172:175], v[206:209], v[16:19]
	v_mfma_f32_16x16x32_bf16 v[8:11], v[180:183], v[206:209], v[8:11]
	v_mfma_f32_16x16x32_bf16 v[4:7], v[172:175], v[214:217], v[4:7]
	v_mfma_f32_16x16x32_bf16 v[0:3], v[180:183], v[214:217], v[0:3]
	s_setprio 0
	s_barrier
	s_add_i32 s62, s62, 2
	s_add_u32 s46, s46, 0x100
	s_addc_u32 s47, s47, 0
	s_add_u32 s60, s60, 0x100
	s_addc_u32 s61, s61, 0
	s_cmp_gt_u32 s62, 13
	s_cbranch_scc0 .LBB0_563
	s_and_b64 vcc, exec, s[18:19]
	s_cbranch_vccz .LBB0_566
	s_barrier

; #define PG8_STAGE(bufoff, gbase, voff) do { _Pragma("unroll") for (int _i = 0; _i < 2; ++_i) \
;         __builtin_amdgcn_global_load_lds((const unsigned*)((const char*)(gbase) + (voff)[_i]), (PG8_LAS unsigned*)(lds + (bufoff) + ldsw + _i * 8192), 16, 0, 0); } while (0)
; #define PG8_LDA(dst, b, h) do { _Pragma("unroll") for (int m = 0; m < 4; ++m) _Pragma("unroll") for (int k = 0; k < 2; ++k) dst[m][k] = *(const PG8_LAS bf16x8*)(lds + PG8_SA(b, h) + aoff + m * 2048 + k * 1024); } while (0)
; #define PG8_LDB(dst, b, h) do { _Pragma("unroll") for (int n = 0; n < 2; ++n) _Pragma("unroll") for (int k = 0; k < 2; ++k) dst[n][k] = *(const PG8_LAS bf16x8*)(lds + PG8_SB(b, h) + boff + n * 2048 + k * 1024); } while (0)
; #define PG8_MMA(ai, bj, At, Bt) do { __builtin_amdgcn_s_setprio(1); _Pragma("unroll") for (int m = 0; m < 4; ++m) _Pragma("unroll") for (int n = 0; n < 2; ++n) _Pragma("unroll") for (int k = 0; k < 2; ++k) \
;         acc[ai][bj][m][n] = __builtin_amdgcn_mfma_f32_16x16x32_bf16(Bt[n][k], At[m][k], acc[ai][bj][m][n], 0, 0, 0); __builtin_amdgcn_s_setprio(0); } while (0)
; #define PG8_WAIT_V(n) asm volatile("s_waitcnt vmcnt(" #n ")" ::: "memory")
; #define PG8_WAIT_L(n) asm volatile("s_waitcnt lgkmcnt(" #n ")" ::: "memory")
; #define PG8_BAR __builtin_amdgcn_s_barrier()
; #define PG8_SCHED __builtin_amdgcn_sched_barrier(0)
; template <class Epi, class Sched, bool ALIGN_EPI = false, bool SP2 = false>
; __device__ __forceinline__ void gemm_phase(PG8_LAS unsigned char* lds, const Gemm g, const Sched& S, const Epi& E) {
;     ...
;             const bool last = (t == nt - 2);
;             const char* a1 = cA + (size_t)(t + 1) * kstep;
;             const char* a2 = last ? nA : cA + (size_t)(t + 2) * kstep; const char* b2 = last ? nB : cB + (size_t)(t + 2) * kstep;
;             const char* a3 = a2 + kstep; const char* b3 = b2 + kstep;
;             if (last && has_next) S.a_ready(nxt);
;             if constexpr (SP2) {
;             PG8_LDB(B0, 0, 0); PG8_LDB(B1, 0, 1); PG8_SCHED; PG8_LDA(At, 0, 0); PG8_STAGE(PG8_SA(1, 1), a1 + hstep, voffA);
;             PG8_WAIT_V(8); PG8_WAIT_L(0); PG8_BAR; PG8_MMA(0, 0, At, B0); PG8_MMA(0, 1, At, B1); PG8_BAR; PG8_SCHED;
;             PG8_LDA(At, 0, 1); PG8_STAGE(PG8_SB(0, 0), b2, voffB); PG8_STAGE(PG8_SB(0, 1), b2 + hstep, voffB); PG8_STAGE(PG8_SA(0, 0), a2, voffA);
.LBB0_645:
	ds_read_b128 v[144:147], v153
	ds_read_b128 v[158:161], v153 offset:1024
	ds_read_b128 v[162:165], v153 offset:2048
	ds_read_b128 v[166:169], v153 offset:3072
	ds_read_b128 v[170:173], v154
	ds_read_b128 v[174:177], v154 offset:1024
	ds_read_b128 v[178:181], v154 offset:2048
	ds_read_b128 v[182:185], v154 offset:3072
	s_add_u32 s54, s48, 0xfffc0080
	s_addc_u32 s55, s49, -1
	s_cmp_eq_u32 s62, 12
	s_cselect_b32 s57, s39, s55
	s_cselect_b32 s56, s45, s54
	s_cselect_b32 s55, s27, s61
	s_cselect_b32 s54, s59, s60
	v_lshl_add_u64 v[148:149], s[48:49], 0, v[136:137]
	s_add_i32 m0, s28, 0xc000
	ds_read_b128 v[186:189], v155
	ds_read_b128 v[190:193], v155 offset:1024
	ds_read_b128 v[194:197], v155 offset:2048
	ds_read_b128 v[198:201], v155 offset:3072
	ds_read_b128 v[206:209], v155 offset:4096
	ds_read_b128 v[210:213], v155 offset:5120
	ds_read_b128 v[214:217], v155 offset:6144
	ds_read_b128 v[218:221], v155 offset:7168
	global_load_lds_dwordx4 v[148:149], off
	v_lshl_add_u64 v[148:149], s[48:49], 0, v[138:139]
	s_add_i32 m0, s28, 0xe000
	s_nop 0
	global_load_lds_dwordx4 v[148:149], off
	s_waitcnt vmcnt(8)
	s_waitcnt lgkmcnt(0)
	s_barrier
	s_setprio 1
	s_waitcnt lgkmcnt(0)
	v_mfma_f32_16x16x32_bf16 v[124:127], v[144:147], v[186:189], v[124:127]
	v_mfma_f32_16x16x32_bf16 v[120:123], v[162:165], v[186:189], v[120:123]
	v_mfma_f32_16x16x32_bf16 v[108:111], v[144:147], v[194:197], v[108:111]
	v_mfma_f32_16x16x32_bf16 v[104:107], v[162:165], v[194:197], v[104:107]
	v_mfma_f32_16x16x32_bf16 v[92:95], v[144:147], v[206:209], v[92:95]
	v_mfma_f32_16x16x32_bf16 v[88:91], v[162:165], v[206:209], v[88:91]
	v_mfma_f32_16x16x32_bf16 v[76:79], v[144:147], v[214:217], v[76:79]
	v_mfma_f32_16x16x32_bf16 v[72:75], v[162:165], v[214:217], v[72:75]
	v_mfma_f32_16x16x32_bf16 v[124:127], v[158:161], v[190:193], v[124:127]
	v_mfma_f32_16x16x32_bf16 v[120:123], v[166:169], v[190:193], v[120:123]
	v_mfma_f32_16x16x32_bf16 v[108:111], v[158:161], v[198:201], v[108:111]
	v_mfma_f32_16x16x32_bf16 v[104:107], v[166:169], v[198:201], v[104:107]
	v_mfma_f32_16x16x32_bf16 v[92:95], v[158:161], v[210:213], v[92:95]
	v_mfma_f32_16x16x32_bf16 v[88:91], v[166:169], v[210:213], v[88:91]
	v_mfma_f32_16x16x32_bf16 v[76:79], v[158:161], v[218:221], v[76:79]
	v_mfma_f32_16x16x32_bf16 v[72:75], v[166:169], v[218:221], v[72:75]
	v_mfma_f32_16x16x32_bf16 v[116:119], v[170:173], v[186:189], v[116:119]
	v_mfma_f32_16x16x32_bf16 v[112:115], v[178:181], v[186:189], v[112:115]
	v_mfma_f32_16x16x32_bf16 v[100:103], v[170:173], v[194:197], v[100:103]
	v_mfma_f32_16x16x32_bf16 v[96:99], v[178:181], v[194:197], v[96:99]
	v_mfma_f32_16x16x32_bf16 v[84:87], v[170:173], v[206:209], v[84:87]
	v_mfma_f32_16x16x32_bf16 v[80:83], v[178:181], v[206:209], v[80:83]
	v_mfma_f32_16x16x32_bf16 v[68:71], v[170:173], v[214:217], v[68:71]
	v_mfma_f32_16x16x32_bf16 v[64:67], v[178:181], v[214:217], v[64:67]
	v_mfma_f32_16x16x32_bf16 v[116:119], v[174:177], v[190:193], v[116:119]
	v_mfma_f32_16x16x32_bf16 v[112:115], v[182:185], v[190:193], v[112:115]
	v_mfma_f32_16x16x32_bf16 v[100:103], v[174:177], v[198:201], v[100:103]
	v_mfma_f32_16x16x32_bf16 v[96:99], v[182:185], v[198:201], v[96:99]
	v_mfma_f32_16x16x32_bf16 v[84:87], v[174:177], v[210:213], v[84:87]
	v_mfma_f32_16x16x32_bf16 v[80:83], v[182:185], v[210:213], v[80:83]
	v_mfma_f32_16x16x32_bf16 v[68:71], v[174:177], v[218:221], v[68:71]
	v_mfma_f32_16x16x32_bf16 v[64:67], v[182:185], v[218:221], v[64:67]
	s_setprio 0
	s_barrier
	s_add_i32 s63, s47, s3
	v_lshl_add_u64 v[148:149], s[54:55], 0, v[130:131]
	s_mov_b32 m0, s63
	ds_read_b128 v[186:189], v155 offset:16384
	ds_read_b128 v[190:193], v155 offset:17408
	ds_read_b128 v[194:197], v155 offset:18432
	ds_read_b128 v[198:201], v155 offset:19456
	ds_read_b128 v[206:209], v155 offset:20480
	ds_read_b128 v[210:213], v155 offset:21504
	ds_read_b128 v[214:217], v155 offset:22528
	ds_read_b128 v[218:221], v155 offset:23552
	global_load_lds_dwordx4 v[148:149], off
	s_add_i32 m0, s63, 0x2000
	s_add_u32 s64, s54, 0x40000
	v_lshl_add_u64 v[202:203], s[54:55], 0, v[134:135]
	s_addc_u32 s65, s55, 0
	s_add_i32 s63, s58, s3
	global_load_lds_dwordx4 v[202:203], off
	v_lshl_add_u64 v[222:223], s[64:65], 0, v[130:131]
	s_mov_b32 m0, s63
	v_lshl_add_u64 v[224:225], s[56:57], 0, v[132:133]
	global_load_lds_dwordx4 v[222:223], off
	v_lshl_add_u64 v[222:223], s[64:65], 0, v[134:135]
	s_add_i32 m0, s63, 0x2000
	s_nop 0
	global_load_lds_dwordx4 v[222:223], off
	v_lshl_add_u64 v[222:223], s[56:57], 0, v[128:129]
	s_mov_b32 m0, s28
	s_nop 0
	global_load_lds_dwordx4 v[222:223], off
	s_mov_b32 m0, s29
	s_nop 0
	global_load_lds_dwordx4 v[224:225], off
	s_waitcnt vmcnt(8)
	s_waitcnt lgkmcnt(0)
	s_barrier
; #define PG8_STAGE(bufoff, gbase, voff) do { _Pragma("unroll") for (int _i = 0; _i < 2; ++_i) \
;         __builtin_amdgcn_global_load_lds((const unsigned*)((const char*)(gbase) + (voff)[_i]), (PG8_LAS unsigned*)(lds + (bufoff) + ldsw + _i * 8192), 16, 0, 0); } while (0)
; #define PG8_LDA(dst, b, h) do { _Pragma("unroll") for (int m = 0; m < 4; ++m) _Pragma("unroll") for (int k = 0; k < 2; ++k) dst[m][k] = *(const PG8_LAS bf16x8*)(lds + PG8_SA(b, h) + aoff + m * 2048 + k * 1024); } while (0)
; #define PG8_LDB(dst, b, h) do { _Pragma("unroll") for (int n = 0; n < 2; ++n) _Pragma("unroll") for (int k = 0; k < 2; ++k) dst[n][k] = *(const PG8_LAS bf16x8*)(lds + PG8_SB(b, h) + boff + n * 2048 + k * 1024); } while (0)
; #define PG8_MMA(ai, bj, At, Bt) do { __builtin_amdgcn_s_setprio(1); _Pragma("unroll") for (int m = 0; m < 4; ++m) _Pragma("unroll") for (int n = 0; n < 2; ++n) _Pragma("unroll") for (int k = 0; k < 2; ++k) \
;         acc[ai][bj][m][n] = __builtin_amdgcn_mfma_f32_16x16x32_bf16(Bt[n][k], At[m][k], acc[ai][bj][m][n], 0, 0, 0); __builtin_amdgcn_s_setprio(0); } while (0)
; #define PG8_WAIT_V(n) asm volatile("s_waitcnt vmcnt(" #n ")" ::: "memory")
; #define PG8_WAIT_L(n) asm volatile("s_waitcnt lgkmcnt(" #n ")" ::: "memory")
; #define PG8_BAR __builtin_amdgcn_s_barrier()
; #define PG8_SCHED __builtin_amdgcn_sched_barrier(0)
; template <class Epi, class Sched, bool ALIGN_EPI = false, bool SP2 = false>
; __device__ __forceinline__ void gemm_phase(PG8_LAS unsigned char* lds, const Gemm g, const Sched& S, const Epi& E) {
;     ...
;             PG8_WAIT_V(8); PG8_WAIT_L(0); PG8_BAR; PG8_MMA(1, 0, At, B0); PG8_MMA(1, 1, At, B1); PG8_BAR; PG8_SCHED;
;             PG8_LDB(B0, 1, 0); PG8_LDB(B1, 1, 1); PG8_SCHED; PG8_LDA(At, 1, 0); PG8_STAGE(PG8_SA(0, 1), a2 + hstep, voffA);
;             PG8_WAIT_V(8); PG8_WAIT_L(0); PG8_BAR; PG8_MMA(0, 0, At, B0); PG8_MMA(0, 1, At, B1); PG8_BAR; PG8_SCHED;
	s_setprio 1
	s_waitcnt lgkmcnt(0)
	v_mfma_f32_16x16x32_bf16 v[60:63], v[144:147], v[186:189], v[60:63]
	v_mfma_f32_16x16x32_bf16 v[56:59], v[162:165], v[186:189], v[56:59]
	v_mfma_f32_16x16x32_bf16 v[44:47], v[144:147], v[194:197], v[44:47]
	v_mfma_f32_16x16x32_bf16 v[40:43], v[162:165], v[194:197], v[40:43]
	v_mfma_f32_16x16x32_bf16 v[28:31], v[144:147], v[206:209], v[28:31]
	v_mfma_f32_16x16x32_bf16 v[24:27], v[162:165], v[206:209], v[24:27]
	v_mfma_f32_16x16x32_bf16 v[12:15], v[144:147], v[214:217], v[12:15]
	v_mfma_f32_16x16x32_bf16 v[8:11], v[162:165], v[214:217], v[8:11]
	v_mfma_f32_16x16x32_bf16 v[60:63], v[158:161], v[190:193], v[60:63]
	v_mfma_f32_16x16x32_bf16 v[56:59], v[166:169], v[190:193], v[56:59]
	v_mfma_f32_16x16x32_bf16 v[44:47], v[158:161], v[198:201], v[44:47]
	v_mfma_f32_16x16x32_bf16 v[40:43], v[166:169], v[198:201], v[40:43]
	v_mfma_f32_16x16x32_bf16 v[28:31], v[158:161], v[210:213], v[28:31]
	v_mfma_f32_16x16x32_bf16 v[24:27], v[166:169], v[210:213], v[24:27]
	v_mfma_f32_16x16x32_bf16 v[12:15], v[158:161], v[218:221], v[12:15]
	v_mfma_f32_16x16x32_bf16 v[8:11], v[166:169], v[218:221], v[8:11]
	v_mfma_f32_16x16x32_bf16 v[52:55], v[170:173], v[186:189], v[52:55]
	v_mfma_f32_16x16x32_bf16 v[48:51], v[178:181], v[186:189], v[48:51]
	v_mfma_f32_16x16x32_bf16 v[36:39], v[170:173], v[194:197], v[36:39]
	v_mfma_f32_16x16x32_bf16 v[32:35], v[178:181], v[194:197], v[32:35]
	v_mfma_f32_16x16x32_bf16 v[20:23], v[170:173], v[206:209], v[20:23]
	v_mfma_f32_16x16x32_bf16 v[16:19], v[178:181], v[206:209], v[16:19]
	v_mfma_f32_16x16x32_bf16 v[4:7], v[170:173], v[214:217], v[4:7]
	v_mfma_f32_16x16x32_bf16 v[0:3], v[178:181], v[214:217], v[0:3]
	v_mfma_f32_16x16x32_bf16 v[52:55], v[174:177], v[190:193], v[52:55]
	v_mfma_f32_16x16x32_bf16 v[48:51], v[182:185], v[190:193], v[48:51]
	v_mfma_f32_16x16x32_bf16 v[36:39], v[174:177], v[198:201], v[36:39]
	v_mfma_f32_16x16x32_bf16 v[32:35], v[182:185], v[198:201], v[32:35]
	v_mfma_f32_16x16x32_bf16 v[20:23], v[174:177], v[210:213], v[20:23]
	v_mfma_f32_16x16x32_bf16 v[16:19], v[182:185], v[210:213], v[16:19]
	v_mfma_f32_16x16x32_bf16 v[4:7], v[174:177], v[218:221], v[4:7]
	v_mfma_f32_16x16x32_bf16 v[0:3], v[182:185], v[218:221], v[0:3]
	s_setprio 0
	s_barrier
	s_add_i32 s63, 0, 0x18000
	v_add_u32_e32 v157, s63, v151
	s_add_i32 s64, 0, 0x1c000
	ds_read_b128 v[144:147], v157
	ds_read_b128 v[158:161], v157 offset:1024
	ds_read_b128 v[162:165], v157 offset:2048
	ds_read_b128 v[166:169], v157 offset:3072
	v_add_u32_e32 v157, s64, v151
	ds_read_b128 v[170:173], v157
	ds_read_b128 v[174:177], v157 offset:1024
	ds_read_b128 v[178:181], v157 offset:2048
	ds_read_b128 v[182:185], v157 offset:3072
	s_add_u32 s56, s56, 0x40000
	s_addc_u32 s57, s57, 0
	s_mov_b32 m0, s30
	v_lshl_add_u64 v[226:227], s[56:57], 0, v[128:129]
	ds_read_b128 v[186:189], v155 offset:32768
	ds_read_b128 v[190:193], v155 offset:33792
	ds_read_b128 v[194:197], v155 offset:34816
	ds_read_b128 v[198:201], v155 offset:35840
	ds_read_b128 v[206:209], v155 offset:36864
	ds_read_b128 v[210:213], v155 offset:37888
	ds_read_b128 v[214:217], v155 offset:38912
	ds_read_b128 v[218:221], v155 offset:39936
	global_load_lds_dwordx4 v[226:227], off
	v_lshl_add_u64 v[226:227], s[56:57], 0, v[132:133]
	s_mov_b32 m0, s31
	s_nop 0
	global_load_lds_dwordx4 v[226:227], off
	s_waitcnt vmcnt(8)
	s_waitcnt lgkmcnt(0)
	s_barrier
	s_setprio 1
	s_waitcnt lgkmcnt(0)
	v_mfma_f32_16x16x32_bf16 v[124:127], v[144:147], v[186:189], v[124:127]
	v_mfma_f32_16x16x32_bf16 v[120:123], v[162:165], v[186:189], v[120:123]
	v_mfma_f32_16x16x32_bf16 v[108:111], v[144:147], v[194:197], v[108:111]
	v_mfma_f32_16x16x32_bf16 v[104:107], v[162:165], v[194:197], v[104:107]
	v_mfma_f32_16x16x32_bf16 v[92:95], v[144:147], v[206:209], v[92:95]
	v_mfma_f32_16x16x32_bf16 v[88:91], v[162:165], v[206:209], v[88:91]
	v_mfma_f32_16x16x32_bf16 v[76:79], v[144:147], v[214:217], v[76:79]
	v_mfma_f32_16x16x32_bf16 v[72:75], v[162:165], v[214:217], v[72:75]
	v_mfma_f32_16x16x32_bf16 v[124:127], v[158:161], v[190:193], v[124:127]
	v_mfma_f32_16x16x32_bf16 v[120:123], v[166:169], v[190:193], v[120:123]
	v_mfma_f32_16x16x32_bf16 v[108:111], v[158:161], v[198:201], v[108:111]
	v_mfma_f32_16x16x32_bf16 v[104:107], v[166:169], v[198:201], v[104:107]
	v_mfma_f32_16x16x32_bf16 v[92:95], v[158:161], v[210:213], v[92:95]
	v_mfma_f32_16x16x32_bf16 v[88:91], v[166:169], v[210:213], v[88:91]
	v_mfma_f32_16x16x32_bf16 v[76:79], v[158:161], v[218:221], v[76:79]
	v_mfma_f32_16x16x32_bf16 v[72:75], v[166:169], v[218:221], v[72:75]
	v_mfma_f32_16x16x32_bf16 v[116:119], v[170:173], v[186:189], v[116:119]
	v_mfma_f32_16x16x32_bf16 v[112:115], v[178:181], v[186:189], v[112:115]
	v_mfma_f32_16x16x32_bf16 v[100:103], v[170:173], v[194:197], v[100:103]
	v_mfma_f32_16x16x32_bf16 v[96:99], v[178:181], v[194:197], v[96:99]
	v_mfma_f32_16x16x32_bf16 v[84:87], v[170:173], v[206:209], v[84:87]
	v_mfma_f32_16x16x32_bf16 v[80:83], v[178:181], v[206:209], v[80:83]
	v_mfma_f32_16x16x32_bf16 v[68:71], v[170:173], v[214:217], v[68:71]
	v_mfma_f32_16x16x32_bf16 v[64:67], v[178:181], v[214:217], v[64:67]
	v_mfma_f32_16x16x32_bf16 v[116:119], v[174:177], v[190:193], v[116:119]
	v_mfma_f32_16x16x32_bf16 v[112:115], v[182:185], v[190:193], v[112:115]
	v_mfma_f32_16x16x32_bf16 v[100:103], v[174:177], v[198:201], v[100:103]
	v_mfma_f32_16x16x32_bf16 v[96:99], v[182:185], v[198:201], v[96:99]
	v_mfma_f32_16x16x32_bf16 v[84:87], v[174:177], v[210:213], v[84:87]
	v_mfma_f32_16x16x32_bf16 v[80:83], v[182:185], v[210:213], v[80:83]
	v_mfma_f32_16x16x32_bf16 v[68:71], v[174:177], v[218:221], v[68:71]
	v_mfma_f32_16x16x32_bf16 v[64:67], v[182:185], v[218:221], v[64:67]
	s_setprio 0
	s_barrier
; #define PG8_STAGE(bufoff, gbase, voff) do { _Pragma("unroll") for (int _i = 0; _i < 2; ++_i) \
;         __builtin_amdgcn_global_load_lds((const unsigned*)((const char*)(gbase) + (voff)[_i]), (PG8_LAS unsigned*)(lds + (bufoff) + ldsw + _i * 8192), 16, 0, 0); } while (0)
; #define PG8_LDA(dst, b, h) do { _Pragma("unroll") for (int m = 0; m < 4; ++m) _Pragma("unroll") for (int k = 0; k < 2; ++k) dst[m][k] = *(const PG8_LAS bf16x8*)(lds + PG8_SA(b, h) + aoff + m * 2048 + k * 1024); } while (0)
; #define PG8_MMA(ai, bj, At, Bt) do { __builtin_amdgcn_s_setprio(1); _Pragma("unroll") for (int m = 0; m < 4; ++m) _Pragma("unroll") for (int n = 0; n < 2; ++n) _Pragma("unroll") for (int k = 0; k < 2; ++k) \
;         acc[ai][bj][m][n] = __builtin_amdgcn_mfma_f32_16x16x32_bf16(Bt[n][k], At[m][k], acc[ai][bj][m][n], 0, 0, 0); __builtin_amdgcn_s_setprio(0); } while (0)
; #define PG8_WAIT_V(n) asm volatile("s_waitcnt vmcnt(" #n ")" ::: "memory")
; #define PG8_WAIT_L(n) asm volatile("s_waitcnt lgkmcnt(" #n ")" ::: "memory")
; #define PG8_BAR __builtin_amdgcn_s_barrier()
; #define PG8_SCHED __builtin_amdgcn_sched_barrier(0)
; template <class Epi, class Sched, bool ALIGN_EPI = false, bool SP2 = false>
; __device__ __forceinline__ void gemm_phase(PG8_LAS unsigned char* lds, const Gemm g, const Sched& S, const Epi& E) {
;     ...
;             PG8_LDA(At, 1, 1); PG8_STAGE(PG8_SB(1, 0), b3, voffB); PG8_STAGE(PG8_SB(1, 1), b3 + hstep, voffB); PG8_STAGE(PG8_SA(1, 0), a3, voffA);
;             PG8_WAIT_V(8); PG8_WAIT_L(0); PG8_BAR; PG8_MMA(1, 0, At, B0); PG8_MMA(1, 1, At, B1); PG8_BAR; PG8_SCHED;
	s_add_i32 s56, s63, s3
	v_lshl_add_u64 v[148:149], v[148:149], 0, s[14:15]
	s_mov_b32 m0, s56
	ds_read_b128 v[186:189], v155 offset:49152
	ds_read_b128 v[190:193], v155 offset:50176
	ds_read_b128 v[194:197], v155 offset:51200
	ds_read_b128 v[198:201], v155 offset:52224
	ds_read_b128 v[206:209], v155 offset:53248
	ds_read_b128 v[210:213], v155 offset:54272
	ds_read_b128 v[214:217], v155 offset:55296
	ds_read_b128 v[218:221], v155 offset:56320
	global_load_lds_dwordx4 v[148:149], off
	s_add_i32 m0, s56, 0x2000
	s_add_u32 s54, s54, 0x40080
	v_lshl_add_u64 v[148:149], v[202:203], 0, s[14:15]
	s_addc_u32 s55, s55, 0
	s_add_i32 s56, s64, s3
	global_load_lds_dwordx4 v[148:149], off
	v_lshl_add_u64 v[148:149], s[54:55], 0, v[130:131]
	s_mov_b32 m0, s56
	s_nop 0
	global_load_lds_dwordx4 v[148:149], off
	v_lshl_add_u64 v[148:149], s[54:55], 0, v[134:135]
	s_add_i32 m0, s56, 0x2000
	s_nop 0
	global_load_lds_dwordx4 v[148:149], off
	v_lshl_add_u64 v[148:149], v[222:223], 0, s[14:15]
	s_mov_b32 m0, s34
	s_nop 0
	global_load_lds_dwordx4 v[148:149], off
	v_lshl_add_u64 v[148:149], v[224:225], 0, s[14:15]
	s_mov_b32 m0, s35
	s_nop 0
	global_load_lds_dwordx4 v[148:149], off
	s_waitcnt vmcnt(8)
	s_waitcnt lgkmcnt(0)
	s_barrier
	s_setprio 1
	s_waitcnt lgkmcnt(0)
	v_mfma_f32_16x16x32_bf16 v[60:63], v[144:147], v[186:189], v[60:63]
	v_mfma_f32_16x16x32_bf16 v[56:59], v[162:165], v[186:189], v[56:59]
	v_mfma_f32_16x16x32_bf16 v[44:47], v[144:147], v[194:197], v[44:47]
	v_mfma_f32_16x16x32_bf16 v[40:43], v[162:165], v[194:197], v[40:43]
	v_mfma_f32_16x16x32_bf16 v[28:31], v[144:147], v[206:209], v[28:31]
	v_mfma_f32_16x16x32_bf16 v[24:27], v[162:165], v[206:209], v[24:27]
	v_mfma_f32_16x16x32_bf16 v[12:15], v[144:147], v[214:217], v[12:15]
	v_mfma_f32_16x16x32_bf16 v[8:11], v[162:165], v[214:217], v[8:11]
	v_mfma_f32_16x16x32_bf16 v[60:63], v[158:161], v[190:193], v[60:63]
	v_mfma_f32_16x16x32_bf16 v[56:59], v[166:169], v[190:193], v[56:59]
	v_mfma_f32_16x16x32_bf16 v[44:47], v[158:161], v[198:201], v[44:47]
	v_mfma_f32_16x16x32_bf16 v[40:43], v[166:169], v[198:201], v[40:43]
	v_mfma_f32_16x16x32_bf16 v[28:31], v[158:161], v[210:213], v[28:31]
	v_mfma_f32_16x16x32_bf16 v[24:27], v[166:169], v[210:213], v[24:27]
	v_mfma_f32_16x16x32_bf16 v[12:15], v[158:161], v[218:221], v[12:15]
	v_mfma_f32_16x16x32_bf16 v[8:11], v[166:169], v[218:221], v[8:11]
	v_mfma_f32_16x16x32_bf16 v[52:55], v[170:173], v[186:189], v[52:55]
	v_mfma_f32_16x16x32_bf16 v[48:51], v[178:181], v[186:189], v[48:51]
	v_mfma_f32_16x16x32_bf16 v[36:39], v[170:173], v[194:197], v[36:39]
	v_mfma_f32_16x16x32_bf16 v[32:35], v[178:181], v[194:197], v[32:35]
	v_mfma_f32_16x16x32_bf16 v[20:23], v[170:173], v[206:209], v[20:23]
	v_mfma_f32_16x16x32_bf16 v[16:19], v[178:181], v[206:209], v[16:19]
	v_mfma_f32_16x16x32_bf16 v[4:7], v[170:173], v[214:217], v[4:7]
	v_mfma_f32_16x16x32_bf16 v[0:3], v[178:181], v[214:217], v[0:3]
	v_mfma_f32_16x16x32_bf16 v[52:55], v[174:177], v[190:193], v[52:55]
	v_mfma_f32_16x16x32_bf16 v[48:51], v[182:185], v[190:193], v[48:51]
	v_mfma_f32_16x16x32_bf16 v[36:39], v[174:177], v[198:201], v[36:39]
	v_mfma_f32_16x16x32_bf16 v[32:35], v[182:185], v[198:201], v[32:35]
	v_mfma_f32_16x16x32_bf16 v[20:23], v[174:177], v[210:213], v[20:23]
	v_mfma_f32_16x16x32_bf16 v[16:19], v[182:185], v[210:213], v[16:19]
	v_mfma_f32_16x16x32_bf16 v[4:7], v[174:177], v[218:221], v[4:7]
	v_mfma_f32_16x16x32_bf16 v[0:3], v[182:185], v[218:221], v[0:3]
	s_setprio 0
	s_barrier
	s_add_i32 s62, s62, 2
	s_add_u32 s48, s48, 0x100
	s_addc_u32 s49, s49, 0
	s_add_u32 s60, s60, 0x100
	s_addc_u32 s61, s61, 0
	s_cmp_gt_u32 s62, 13
	s_cbranch_scc0 .LBB0_645
	s_and_b64 vcc, exec, s[16:17]
	s_cbranch_vccz .LBB0_648
	s_barrier

; #define PG8_STAGE(bufoff, gbase, voff) do { _Pragma("unroll") for (int _i = 0; _i < 2; ++_i) \
;         __builtin_amdgcn_global_load_lds((const unsigned*)((const char*)(gbase) + (voff)[_i]), (PG8_LAS unsigned*)(lds + (bufoff) + ldsw + _i * 8192), 16, 0, 0); } while (0)
; #define PG8_LDA(dst, b, h) do { _Pragma("unroll") for (int m = 0; m < 4; ++m) _Pragma("unroll") for (int k = 0; k < 2; ++k) dst[m][k] = *(const PG8_LAS bf16x8*)(lds + PG8_SA(b, h) + aoff + m * 2048 + k * 1024); } while (0)
; #define PG8_LDB(dst, b, h) do { _Pragma("unroll") for (int n = 0; n < 2; ++n) _Pragma("unroll") for (int k = 0; k < 2; ++k) dst[n][k] = *(const PG8_LAS bf16x8*)(lds + PG8_SB(b, h) + boff + n * 2048 + k * 1024); } while (0)
; #define PG8_MMA(ai, bj, At, Bt) do { __builtin_amdgcn_s_setprio(1); _Pragma("unroll") for (int m = 0; m < 4; ++m) _Pragma("unroll") for (int n = 0; n < 2; ++n) _Pragma("unroll") for (int k = 0; k < 2; ++k) \
;         acc[ai][bj][m][n] = __builtin_amdgcn_mfma_f32_16x16x32_bf16(Bt[n][k], At[m][k], acc[ai][bj][m][n], 0, 0, 0); __builtin_amdgcn_s_setprio(0); } while (0)
; #define PG8_WAIT_V(n) asm volatile("s_waitcnt vmcnt(" #n ")" ::: "memory")
; #define PG8_WAIT_L(n) asm volatile("s_waitcnt lgkmcnt(" #n ")" ::: "memory")
; #define PG8_BAR __builtin_amdgcn_s_barrier()
; #define PG8_SCHED __builtin_amdgcn_sched_barrier(0)
; template <class Epi, class Sched, bool ALIGN_EPI = false, bool SP2 = false>
; __device__ __forceinline__ void gemm_phase(PG8_LAS unsigned char* lds, const Gemm g, const Sched& S, const Epi& E) {
;     ...
;             const bool last = (t == nt - 2);
;             const char* a1 = cA + (size_t)(t + 1) * kstep;
;             const char* a2 = last ? nA : cA + (size_t)(t + 2) * kstep; const char* b2 = last ? nB : cB + (size_t)(t + 2) * kstep;
;             const char* a3 = a2 + kstep; const char* b3 = b2 + kstep;
;             if (last && has_next) S.a_ready(nxt);
;             if constexpr (SP2) {
;             PG8_LDB(B0, 0, 0); PG8_LDB(B1, 0, 1); PG8_SCHED; PG8_LDA(At, 0, 0); PG8_STAGE(PG8_SA(1, 1), a1 + hstep, voffA);
;             PG8_WAIT_V(8); PG8_WAIT_L(0); PG8_BAR; PG8_MMA(0, 0, At, B0); PG8_MMA(0, 1, At, B1); PG8_BAR; PG8_SCHED;
;             PG8_LDA(At, 0, 1); PG8_STAGE(PG8_SB(0, 0), b2, voffB); PG8_STAGE(PG8_SB(0, 1), b2 + hstep, voffB); PG8_STAGE(PG8_SA(0, 0), a2, voffA);
.LBB0_737:
	ds_read_b128 v[144:147], v155
	ds_read_b128 v[148:151], v155 offset:1024
	ds_read_b128 v[160:163], v155 offset:2048
	ds_read_b128 v[164:167], v155 offset:3072
	ds_read_b128 v[168:171], v156
	ds_read_b128 v[172:175], v156 offset:1024
	ds_read_b128 v[176:179], v156 offset:2048
	ds_read_b128 v[180:183], v156 offset:3072
	s_add_u32 s44, s42, 0xfffc0080
	s_addc_u32 s45, s43, -1
	s_cmp_eq_u32 s60, 12
	s_cselect_b32 s47, s25, s45
	s_cselect_b32 s46, s56, s44
	s_cselect_b32 s45, s23, s59
	s_cselect_b32 s44, s57, s58
	v_lshl_add_u64 v[218:219], s[42:43], 0, v[136:137]
	s_add_i32 m0, s28, 0xc000
	ds_read_b128 v[184:187], v157
	ds_read_b128 v[188:191], v157 offset:1024
	ds_read_b128 v[192:195], v157 offset:2048
	ds_read_b128 v[196:199], v157 offset:3072
	ds_read_b128 v[200:203], v157 offset:4096
	ds_read_b128 v[206:209], v157 offset:5120
	ds_read_b128 v[210:213], v157 offset:6144
	ds_read_b128 v[214:217], v157 offset:7168
	global_load_lds_dwordx4 v[218:219], off
	v_lshl_add_u64 v[218:219], s[42:43], 0, v[138:139]
	s_add_i32 m0, s28, 0xe000
	s_nop 0
	global_load_lds_dwordx4 v[218:219], off
	s_waitcnt vmcnt(8)
	s_waitcnt lgkmcnt(0)
	s_barrier
	s_setprio 1
	s_waitcnt lgkmcnt(0)
	v_mfma_f32_16x16x32_bf16 v[124:127], v[144:147], v[184:187], v[124:127]
	v_mfma_f32_16x16x32_bf16 v[120:123], v[160:163], v[184:187], v[120:123]
	v_mfma_f32_16x16x32_bf16 v[108:111], v[144:147], v[192:195], v[108:111]
	v_mfma_f32_16x16x32_bf16 v[104:107], v[160:163], v[192:195], v[104:107]
	v_mfma_f32_16x16x32_bf16 v[92:95], v[144:147], v[200:203], v[92:95]
	v_mfma_f32_16x16x32_bf16 v[88:91], v[160:163], v[200:203], v[88:91]
	v_mfma_f32_16x16x32_bf16 v[76:79], v[144:147], v[210:213], v[76:79]
	v_mfma_f32_16x16x32_bf16 v[72:75], v[160:163], v[210:213], v[72:75]
	v_mfma_f32_16x16x32_bf16 v[124:127], v[148:151], v[188:191], v[124:127]
	v_mfma_f32_16x16x32_bf16 v[120:123], v[164:167], v[188:191], v[120:123]
	v_mfma_f32_16x16x32_bf16 v[108:111], v[148:151], v[196:199], v[108:111]
	v_mfma_f32_16x16x32_bf16 v[104:107], v[164:167], v[196:199], v[104:107]
	v_mfma_f32_16x16x32_bf16 v[92:95], v[148:151], v[206:209], v[92:95]
	v_mfma_f32_16x16x32_bf16 v[88:91], v[164:167], v[206:209], v[88:91]
	v_mfma_f32_16x16x32_bf16 v[76:79], v[148:151], v[214:217], v[76:79]
	v_mfma_f32_16x16x32_bf16 v[72:75], v[164:167], v[214:217], v[72:75]
	v_mfma_f32_16x16x32_bf16 v[116:119], v[168:171], v[184:187], v[116:119]
	v_mfma_f32_16x16x32_bf16 v[112:115], v[176:179], v[184:187], v[112:115]
	v_mfma_f32_16x16x32_bf16 v[100:103], v[168:171], v[192:195], v[100:103]
	v_mfma_f32_16x16x32_bf16 v[96:99], v[176:179], v[192:195], v[96:99]
	v_mfma_f32_16x16x32_bf16 v[84:87], v[168:171], v[200:203], v[84:87]
	v_mfma_f32_16x16x32_bf16 v[80:83], v[176:179], v[200:203], v[80:83]
	v_mfma_f32_16x16x32_bf16 v[68:71], v[168:171], v[210:213], v[68:71]
	v_mfma_f32_16x16x32_bf16 v[64:67], v[176:179], v[210:213], v[64:67]
	v_mfma_f32_16x16x32_bf16 v[116:119], v[172:175], v[188:191], v[116:119]
	v_mfma_f32_16x16x32_bf16 v[112:115], v[180:183], v[188:191], v[112:115]
	v_mfma_f32_16x16x32_bf16 v[100:103], v[172:175], v[196:199], v[100:103]
	v_mfma_f32_16x16x32_bf16 v[96:99], v[180:183], v[196:199], v[96:99]
	v_mfma_f32_16x16x32_bf16 v[84:87], v[172:175], v[206:209], v[84:87]
	v_mfma_f32_16x16x32_bf16 v[80:83], v[180:183], v[206:209], v[80:83]
	v_mfma_f32_16x16x32_bf16 v[68:71], v[172:175], v[214:217], v[68:71]
	v_mfma_f32_16x16x32_bf16 v[64:67], v[180:183], v[214:217], v[64:67]
	s_setprio 0
	s_barrier
	s_add_i32 s61, s41, s3
	v_lshl_add_u64 v[218:219], s[44:45], 0, v[130:131]
	s_mov_b32 m0, s61
	ds_read_b128 v[184:187], v157 offset:16384
	ds_read_b128 v[188:191], v157 offset:17408
	ds_read_b128 v[192:195], v157 offset:18432
	ds_read_b128 v[196:199], v157 offset:19456
	ds_read_b128 v[200:203], v157 offset:20480
	ds_read_b128 v[206:209], v157 offset:21504
	ds_read_b128 v[210:213], v157 offset:22528
	ds_read_b128 v[214:217], v157 offset:23552
	global_load_lds_dwordx4 v[218:219], off
	s_add_i32 m0, s61, 0x2000
	s_add_u32 s62, s44, 0x40000
	v_lshl_add_u64 v[220:221], s[44:45], 0, v[134:135]
	s_addc_u32 s63, s45, 0
	s_add_i32 s61, s48, s3
	global_load_lds_dwordx4 v[220:221], off
	v_lshl_add_u64 v[222:223], s[62:63], 0, v[130:131]
	s_mov_b32 m0, s61
	v_lshl_add_u64 v[224:225], s[46:47], 0, v[132:133]
	global_load_lds_dwordx4 v[222:223], off
	v_lshl_add_u64 v[222:223], s[62:63], 0, v[134:135]
	s_add_i32 m0, s61, 0x2000
	s_nop 0
	global_load_lds_dwordx4 v[222:223], off
	v_lshl_add_u64 v[222:223], s[46:47], 0, v[128:129]
	s_mov_b32 m0, s28
	s_nop 0
	global_load_lds_dwordx4 v[222:223], off
	s_mov_b32 m0, s29
	s_nop 0
	global_load_lds_dwordx4 v[224:225], off
	s_waitcnt vmcnt(8)
	s_waitcnt lgkmcnt(0)
	s_barrier
; #define PG8_STAGE(bufoff, gbase, voff) do { _Pragma("unroll") for (int _i = 0; _i < 2; ++_i) \
;         __builtin_amdgcn_global_load_lds((const unsigned*)((const char*)(gbase) + (voff)[_i]), (PG8_LAS unsigned*)(lds + (bufoff) + ldsw + _i * 8192), 16, 0, 0); } while (0)
; #define PG8_LDA(dst, b, h) do { _Pragma("unroll") for (int m = 0; m < 4; ++m) _Pragma("unroll") for (int k = 0; k < 2; ++k) dst[m][k] = *(const PG8_LAS bf16x8*)(lds + PG8_SA(b, h) + aoff + m * 2048 + k * 1024); } while (0)
; #define PG8_LDB(dst, b, h) do { _Pragma("unroll") for (int n = 0; n < 2; ++n) _Pragma("unroll") for (int k = 0; k < 2; ++k) dst[n][k] = *(const PG8_LAS bf16x8*)(lds + PG8_SB(b, h) + boff + n * 2048 + k * 1024); } while (0)
; #define PG8_MMA(ai, bj, At, Bt) do { __builtin_amdgcn_s_setprio(1); _Pragma("unroll") for (int m = 0; m < 4; ++m) _Pragma("unroll") for (int n = 0; n < 2; ++n) _Pragma("unroll") for (int k = 0; k < 2; ++k) \
;         acc[ai][bj][m][n] = __builtin_amdgcn_mfma_f32_16x16x32_bf16(Bt[n][k], At[m][k], acc[ai][bj][m][n], 0, 0, 0); __builtin_amdgcn_s_setprio(0); } while (0)
; #define PG8_WAIT_V(n) asm volatile("s_waitcnt vmcnt(" #n ")" ::: "memory")
; #define PG8_WAIT_L(n) asm volatile("s_waitcnt lgkmcnt(" #n ")" ::: "memory")
; #define PG8_BAR __builtin_amdgcn_s_barrier()
; #define PG8_SCHED __builtin_amdgcn_sched_barrier(0)
; template <class Epi, class Sched, bool ALIGN_EPI = false, bool SP2 = false>
; __device__ __forceinline__ void gemm_phase(PG8_LAS unsigned char* lds, const Gemm g, const Sched& S, const Epi& E) {
;     ...
;             PG8_WAIT_V(8); PG8_WAIT_L(0); PG8_BAR; PG8_MMA(1, 0, At, B0); PG8_MMA(1, 1, At, B1); PG8_BAR; PG8_SCHED;
;             PG8_LDB(B0, 1, 0); PG8_LDB(B1, 1, 1); PG8_SCHED; PG8_LDA(At, 1, 0); PG8_STAGE(PG8_SA(0, 1), a2 + hstep, voffA);
;             PG8_WAIT_V(8); PG8_WAIT_L(0); PG8_BAR; PG8_MMA(0, 0, At, B0); PG8_MMA(0, 1, At, B1); PG8_BAR; PG8_SCHED;
	s_setprio 1
	s_waitcnt lgkmcnt(0)
	v_mfma_f32_16x16x32_bf16 v[60:63], v[144:147], v[184:187], v[60:63]
	v_mfma_f32_16x16x32_bf16 v[56:59], v[160:163], v[184:187], v[56:59]
	v_mfma_f32_16x16x32_bf16 v[44:47], v[144:147], v[192:195], v[44:47]
	v_mfma_f32_16x16x32_bf16 v[40:43], v[160:163], v[192:195], v[40:43]
	v_mfma_f32_16x16x32_bf16 v[28:31], v[144:147], v[200:203], v[28:31]
	v_mfma_f32_16x16x32_bf16 v[24:27], v[160:163], v[200:203], v[24:27]
	v_mfma_f32_16x16x32_bf16 v[12:15], v[144:147], v[210:213], v[12:15]
	v_mfma_f32_16x16x32_bf16 v[8:11], v[160:163], v[210:213], v[8:11]
	v_mfma_f32_16x16x32_bf16 v[60:63], v[148:151], v[188:191], v[60:63]
	v_mfma_f32_16x16x32_bf16 v[56:59], v[164:167], v[188:191], v[56:59]
	v_mfma_f32_16x16x32_bf16 v[44:47], v[148:151], v[196:199], v[44:47]
	v_mfma_f32_16x16x32_bf16 v[40:43], v[164:167], v[196:199], v[40:43]
	v_mfma_f32_16x16x32_bf16 v[28:31], v[148:151], v[206:209], v[28:31]
	v_mfma_f32_16x16x32_bf16 v[24:27], v[164:167], v[206:209], v[24:27]
	v_mfma_f32_16x16x32_bf16 v[12:15], v[148:151], v[214:217], v[12:15]
	v_mfma_f32_16x16x32_bf16 v[8:11], v[164:167], v[214:217], v[8:11]
	v_mfma_f32_16x16x32_bf16 v[52:55], v[168:171], v[184:187], v[52:55]
	v_mfma_f32_16x16x32_bf16 v[48:51], v[176:179], v[184:187], v[48:51]
	v_mfma_f32_16x16x32_bf16 v[36:39], v[168:171], v[192:195], v[36:39]
	v_mfma_f32_16x16x32_bf16 v[32:35], v[176:179], v[192:195], v[32:35]
	v_mfma_f32_16x16x32_bf16 v[20:23], v[168:171], v[200:203], v[20:23]
	v_mfma_f32_16x16x32_bf16 v[16:19], v[176:179], v[200:203], v[16:19]
	v_mfma_f32_16x16x32_bf16 v[4:7], v[168:171], v[210:213], v[4:7]
	v_mfma_f32_16x16x32_bf16 v[0:3], v[176:179], v[210:213], v[0:3]
	v_mfma_f32_16x16x32_bf16 v[52:55], v[172:175], v[188:191], v[52:55]
	v_mfma_f32_16x16x32_bf16 v[48:51], v[180:183], v[188:191], v[48:51]
	v_mfma_f32_16x16x32_bf16 v[36:39], v[172:175], v[196:199], v[36:39]
	v_mfma_f32_16x16x32_bf16 v[32:35], v[180:183], v[196:199], v[32:35]
	v_mfma_f32_16x16x32_bf16 v[20:23], v[172:175], v[206:209], v[20:23]
	v_mfma_f32_16x16x32_bf16 v[16:19], v[180:183], v[206:209], v[16:19]
	v_mfma_f32_16x16x32_bf16 v[4:7], v[172:175], v[214:217], v[4:7]
	v_mfma_f32_16x16x32_bf16 v[0:3], v[180:183], v[214:217], v[0:3]
	s_setprio 0
	s_barrier
	s_add_i32 s61, 0, 0x18000
	v_add_u32_e32 v159, s61, v153
	s_add_i32 s62, 0, 0x1c000
	ds_read_b128 v[144:147], v159
	ds_read_b128 v[148:151], v159 offset:1024
	ds_read_b128 v[160:163], v159 offset:2048
	ds_read_b128 v[164:167], v159 offset:3072
	v_add_u32_e32 v159, s62, v153
	ds_read_b128 v[168:171], v159
	ds_read_b128 v[172:175], v159 offset:1024
	ds_read_b128 v[176:179], v159 offset:2048
	ds_read_b128 v[180:183], v159 offset:3072
	s_add_u32 s46, s46, 0x40000
	s_addc_u32 s47, s47, 0
	s_mov_b32 m0, s30
	v_lshl_add_u64 v[226:227], s[46:47], 0, v[128:129]
	ds_read_b128 v[184:187], v157 offset:32768
	ds_read_b128 v[188:191], v157 offset:33792
	ds_read_b128 v[192:195], v157 offset:34816
	ds_read_b128 v[196:199], v157 offset:35840
	ds_read_b128 v[200:203], v157 offset:36864
	ds_read_b128 v[206:209], v157 offset:37888
	ds_read_b128 v[210:213], v157 offset:38912
	ds_read_b128 v[214:217], v157 offset:39936
	global_load_lds_dwordx4 v[226:227], off
	v_lshl_add_u64 v[226:227], s[46:47], 0, v[132:133]
	s_mov_b32 m0, s31
	s_nop 0
	global_load_lds_dwordx4 v[226:227], off
	s_waitcnt vmcnt(8)
	s_waitcnt lgkmcnt(0)
	s_barrier
	s_setprio 1
	s_waitcnt lgkmcnt(0)
	v_mfma_f32_16x16x32_bf16 v[124:127], v[144:147], v[184:187], v[124:127]
	v_mfma_f32_16x16x32_bf16 v[120:123], v[160:163], v[184:187], v[120:123]
	v_mfma_f32_16x16x32_bf16 v[108:111], v[144:147], v[192:195], v[108:111]
	v_mfma_f32_16x16x32_bf16 v[104:107], v[160:163], v[192:195], v[104:107]
	v_mfma_f32_16x16x32_bf16 v[92:95], v[144:147], v[200:203], v[92:95]
	v_mfma_f32_16x16x32_bf16 v[88:91], v[160:163], v[200:203], v[88:91]
	v_mfma_f32_16x16x32_bf16 v[76:79], v[144:147], v[210:213], v[76:79]
	v_mfma_f32_16x16x32_bf16 v[72:75], v[160:163], v[210:213], v[72:75]
	v_mfma_f32_16x16x32_bf16 v[124:127], v[148:151], v[188:191], v[124:127]
	v_mfma_f32_16x16x32_bf16 v[120:123], v[164:167], v[188:191], v[120:123]
	v_mfma_f32_16x16x32_bf16 v[108:111], v[148:151], v[196:199], v[108:111]
	v_mfma_f32_16x16x32_bf16 v[104:107], v[164:167], v[196:199], v[104:107]
	v_mfma_f32_16x16x32_bf16 v[92:95], v[148:151], v[206:209], v[92:95]
	v_mfma_f32_16x16x32_bf16 v[88:91], v[164:167], v[206:209], v[88:91]
	v_mfma_f32_16x16x32_bf16 v[76:79], v[148:151], v[214:217], v[76:79]
	v_mfma_f32_16x16x32_bf16 v[72:75], v[164:167], v[214:217], v[72:75]
	v_mfma_f32_16x16x32_bf16 v[116:119], v[168:171], v[184:187], v[116:119]
	v_mfma_f32_16x16x32_bf16 v[112:115], v[176:179], v[184:187], v[112:115]
	v_mfma_f32_16x16x32_bf16 v[100:103], v[168:171], v[192:195], v[100:103]
	v_mfma_f32_16x16x32_bf16 v[96:99], v[176:179], v[192:195], v[96:99]
	v_mfma_f32_16x16x32_bf16 v[84:87], v[168:171], v[200:203], v[84:87]
	v_mfma_f32_16x16x32_bf16 v[80:83], v[176:179], v[200:203], v[80:83]
	v_mfma_f32_16x16x32_bf16 v[68:71], v[168:171], v[210:213], v[68:71]
	v_mfma_f32_16x16x32_bf16 v[64:67], v[176:179], v[210:213], v[64:67]
	v_mfma_f32_16x16x32_bf16 v[116:119], v[172:175], v[188:191], v[116:119]
	v_mfma_f32_16x16x32_bf16 v[112:115], v[180:183], v[188:191], v[112:115]
	v_mfma_f32_16x16x32_bf16 v[100:103], v[172:175], v[196:199], v[100:103]
	v_mfma_f32_16x16x32_bf16 v[96:99], v[180:183], v[196:199], v[96:99]
	v_mfma_f32_16x16x32_bf16 v[84:87], v[172:175], v[206:209], v[84:87]
	v_mfma_f32_16x16x32_bf16 v[80:83], v[180:183], v[206:209], v[80:83]
	v_mfma_f32_16x16x32_bf16 v[68:71], v[172:175], v[214:217], v[68:71]
	v_mfma_f32_16x16x32_bf16 v[64:67], v[180:183], v[214:217], v[64:67]
	s_setprio 0
	s_barrier
; #define PG8_STAGE(bufoff, gbase, voff) do { _Pragma("unroll") for (int _i = 0; _i < 2; ++_i) \
;         __builtin_amdgcn_global_load_lds((const unsigned*)((const char*)(gbase) + (voff)[_i]), (PG8_LAS unsigned*)(lds + (bufoff) + ldsw + _i * 8192), 16, 0, 0); } while (0)
; #define PG8_LDA(dst, b, h) do { _Pragma("unroll") for (int m = 0; m < 4; ++m) _Pragma("unroll") for (int k = 0; k < 2; ++k) dst[m][k] = *(const PG8_LAS bf16x8*)(lds + PG8_SA(b, h) + aoff + m * 2048 + k * 1024); } while (0)
; #define PG8_MMA(ai, bj, At, Bt) do { __builtin_amdgcn_s_setprio(1); _Pragma("unroll") for (int m = 0; m < 4; ++m) _Pragma("unroll") for (int n = 0; n < 2; ++n) _Pragma("unroll") for (int k = 0; k < 2; ++k) \
;         acc[ai][bj][m][n] = __builtin_amdgcn_mfma_f32_16x16x32_bf16(Bt[n][k], At[m][k], acc[ai][bj][m][n], 0, 0, 0); __builtin_amdgcn_s_setprio(0); } while (0)
; #define PG8_WAIT_V(n) asm volatile("s_waitcnt vmcnt(" #n ")" ::: "memory")
; #define PG8_WAIT_L(n) asm volatile("s_waitcnt lgkmcnt(" #n ")" ::: "memory")
; #define PG8_BAR __builtin_amdgcn_s_barrier()
; #define PG8_SCHED __builtin_amdgcn_sched_barrier(0)
; template <class Epi, class Sched, bool ALIGN_EPI = false, bool SP2 = false>
; __device__ __forceinline__ void gemm_phase(PG8_LAS unsigned char* lds, const Gemm g, const Sched& S, const Epi& E) {
;     ...
;             PG8_LDA(At, 1, 1); PG8_STAGE(PG8_SB(1, 0), b3, voffB); PG8_STAGE(PG8_SB(1, 1), b3 + hstep, voffB); PG8_STAGE(PG8_SA(1, 0), a3, voffA);
;             PG8_WAIT_V(8); PG8_WAIT_L(0); PG8_BAR; PG8_MMA(1, 0, At, B0); PG8_MMA(1, 1, At, B1); PG8_BAR; PG8_SCHED;
	s_add_i32 s46, s61, s3
	v_lshl_add_u64 v[218:219], v[218:219], 0, s[10:11]
	s_mov_b32 m0, s46
	ds_read_b128 v[184:187], v157 offset:49152
	ds_read_b128 v[188:191], v157 offset:50176
	ds_read_b128 v[192:195], v157 offset:51200
	ds_read_b128 v[196:199], v157 offset:52224
	ds_read_b128 v[200:203], v157 offset:53248
	ds_read_b128 v[206:209], v157 offset:54272
	ds_read_b128 v[210:213], v157 offset:55296
	ds_read_b128 v[214:217], v157 offset:56320
	global_load_lds_dwordx4 v[218:219], off
	s_add_i32 m0, s46, 0x2000
	s_add_u32 s44, s44, 0x40080
	v_lshl_add_u64 v[218:219], v[220:221], 0, s[10:11]
	s_addc_u32 s45, s45, 0
	s_add_i32 s46, s62, s3
	global_load_lds_dwordx4 v[218:219], off
	v_lshl_add_u64 v[218:219], s[44:45], 0, v[130:131]
	s_mov_b32 m0, s46
	s_nop 0
	global_load_lds_dwordx4 v[218:219], off
	v_lshl_add_u64 v[218:219], s[44:45], 0, v[134:135]
	s_add_i32 m0, s46, 0x2000
	s_nop 0
	global_load_lds_dwordx4 v[218:219], off
	v_lshl_add_u64 v[218:219], v[222:223], 0, s[10:11]
	s_mov_b32 m0, s34
	s_nop 0
	global_load_lds_dwordx4 v[218:219], off
	v_lshl_add_u64 v[218:219], v[224:225], 0, s[10:11]
	s_mov_b32 m0, s35
	s_nop 0
	global_load_lds_dwordx4 v[218:219], off
	s_waitcnt vmcnt(8)
	s_waitcnt lgkmcnt(0)
	s_barrier
	s_setprio 1
	s_waitcnt lgkmcnt(0)
	v_mfma_f32_16x16x32_bf16 v[60:63], v[144:147], v[184:187], v[60:63]
	v_mfma_f32_16x16x32_bf16 v[56:59], v[160:163], v[184:187], v[56:59]
	v_mfma_f32_16x16x32_bf16 v[44:47], v[144:147], v[192:195], v[44:47]
	v_mfma_f32_16x16x32_bf16 v[40:43], v[160:163], v[192:195], v[40:43]
	v_mfma_f32_16x16x32_bf16 v[28:31], v[144:147], v[200:203], v[28:31]
	v_mfma_f32_16x16x32_bf16 v[24:27], v[160:163], v[200:203], v[24:27]
	v_mfma_f32_16x16x32_bf16 v[12:15], v[144:147], v[210:213], v[12:15]
	v_mfma_f32_16x16x32_bf16 v[8:11], v[160:163], v[210:213], v[8:11]
	v_mfma_f32_16x16x32_bf16 v[60:63], v[148:151], v[188:191], v[60:63]
	v_mfma_f32_16x16x32_bf16 v[56:59], v[164:167], v[188:191], v[56:59]
	v_mfma_f32_16x16x32_bf16 v[44:47], v[148:151], v[196:199], v[44:47]
	v_mfma_f32_16x16x32_bf16 v[40:43], v[164:167], v[196:199], v[40:43]
	v_mfma_f32_16x16x32_bf16 v[28:31], v[148:151], v[206:209], v[28:31]
	v_mfma_f32_16x16x32_bf16 v[24:27], v[164:167], v[206:209], v[24:27]
	v_mfma_f32_16x16x32_bf16 v[12:15], v[148:151], v[214:217], v[12:15]
	v_mfma_f32_16x16x32_bf16 v[8:11], v[164:167], v[214:217], v[8:11]
	v_mfma_f32_16x16x32_bf16 v[52:55], v[168:171], v[184:187], v[52:55]
	v_mfma_f32_16x16x32_bf16 v[48:51], v[176:179], v[184:187], v[48:51]
	v_mfma_f32_16x16x32_bf16 v[36:39], v[168:171], v[192:195], v[36:39]
	v_mfma_f32_16x16x32_bf16 v[32:35], v[176:179], v[192:195], v[32:35]
	v_mfma_f32_16x16x32_bf16 v[20:23], v[168:171], v[200:203], v[20:23]
	v_mfma_f32_16x16x32_bf16 v[16:19], v[176:179], v[200:203], v[16:19]
	v_mfma_f32_16x16x32_bf16 v[4:7], v[168:171], v[210:213], v[4:7]
	v_mfma_f32_16x16x32_bf16 v[0:3], v[176:179], v[210:213], v[0:3]
	v_mfma_f32_16x16x32_bf16 v[52:55], v[172:175], v[188:191], v[52:55]
	v_mfma_f32_16x16x32_bf16 v[48:51], v[180:183], v[188:191], v[48:51]
	v_mfma_f32_16x16x32_bf16 v[36:39], v[172:175], v[196:199], v[36:39]
	v_mfma_f32_16x16x32_bf16 v[32:35], v[180:183], v[196:199], v[32:35]
	v_mfma_f32_16x16x32_bf16 v[20:23], v[172:175], v[206:209], v[20:23]
	v_mfma_f32_16x16x32_bf16 v[16:19], v[180:183], v[206:209], v[16:19]
	v_mfma_f32_16x16x32_bf16 v[4:7], v[172:175], v[214:217], v[4:7]
	v_mfma_f32_16x16x32_bf16 v[0:3], v[180:183], v[214:217], v[0:3]
	s_setprio 0
	s_barrier
	s_add_i32 s60, s60, 2
	s_add_u32 s42, s42, 0x100
	s_addc_u32 s43, s43, 0
	s_add_u32 s58, s58, 0x100
	s_addc_u32 s59, s59, 0
	s_cmp_gt_u32 s60, 13
	s_cbranch_scc0 .LBB0_737
	s_and_b64 vcc, exec, s[12:13]
	s_cbranch_vccz .LBB0_740
	s_barrier

; #define PG8_STAGE(bufoff, gbase, voff) do { _Pragma("unroll") for (int _i = 0; _i < 2; ++_i) \
;         __builtin_amdgcn_global_load_lds((const unsigned*)((const char*)(gbase) + (voff)[_i]), (PG8_LAS unsigned*)(lds + (bufoff) + ldsw + _i * 8192), 16, 0, 0); } while (0)
; #define PG8_LDA(dst, b, h) do { _Pragma("unroll") for (int m = 0; m < 4; ++m) _Pragma("unroll") for (int k = 0; k < 2; ++k) dst[m][k] = *(const PG8_LAS bf16x8*)(lds + PG8_SA(b, h) + aoff + m * 2048 + k * 1024); } while (0)
; #define PG8_LDB(dst, b, h) do { _Pragma("unroll") for (int n = 0; n < 2; ++n) _Pragma("unroll") for (int k = 0; k < 2; ++k) dst[n][k] = *(const PG8_LAS bf16x8*)(lds + PG8_SB(b, h) + boff + n * 2048 + k * 1024); } while (0)
; #define PG8_MMA(ai, bj, At, Bt) do { __builtin_amdgcn_s_setprio(1); _Pragma("unroll") for (int m = 0; m < 4; ++m) _Pragma("unroll") for (int n = 0; n < 2; ++n) _Pragma("unroll") for (int k = 0; k < 2; ++k) \
;         acc[ai][bj][m][n] = __builtin_amdgcn_mfma_f32_16x16x32_bf16(Bt[n][k], At[m][k], acc[ai][bj][m][n], 0, 0, 0); __builtin_amdgcn_s_setprio(0); } while (0)
; #define PG8_WAIT_V(n) asm volatile("s_waitcnt vmcnt(" #n ")" ::: "memory")
; #define PG8_WAIT_L(n) asm volatile("s_waitcnt lgkmcnt(" #n ")" ::: "memory")
; #define PG8_BAR __builtin_amdgcn_s_barrier()
; #define PG8_SCHED __builtin_amdgcn_sched_barrier(0)
; template <class Epi, class Sched, bool ALIGN_EPI = false, bool SP2 = false>
; __device__ __forceinline__ void gemm_phase(PG8_LAS unsigned char* lds, const Gemm g, const Sched& S, const Epi& E) {
;     ...
;             const bool last = (t == nt - 2);
;             const char* a1 = cA + (size_t)(t + 1) * kstep;
;             const char* a2 = last ? nA : cA + (size_t)(t + 2) * kstep; const char* b2 = last ? nB : cB + (size_t)(t + 2) * kstep;
;             const char* a3 = a2 + kstep; const char* b3 = b2 + kstep;
;             if (last && has_next) S.a_ready(nxt);
;             if constexpr (SP2) {
;             PG8_LDB(B0, 0, 0); PG8_LDB(B1, 0, 1); PG8_SCHED; PG8_LDA(At, 0, 0); PG8_STAGE(PG8_SA(1, 1), a1 + hstep, voffA);
;             PG8_WAIT_V(8); PG8_WAIT_L(0); PG8_BAR; PG8_MMA(0, 0, At, B0); PG8_MMA(0, 1, At, B1); PG8_BAR; PG8_SCHED;
;             PG8_LDA(At, 0, 1); PG8_STAGE(PG8_SB(0, 0), b2, voffB); PG8_STAGE(PG8_SB(0, 1), b2 + hstep, voffB); PG8_STAGE(PG8_SA(0, 0), a2, voffA);
.LBB0_813:
	ds_read_b128 v[144:147], v153
	ds_read_b128 v[156:159], v153 offset:1024
	ds_read_b128 v[160:163], v153 offset:2048
	ds_read_b128 v[164:167], v153 offset:3072
	ds_read_b128 v[168:171], v154
	ds_read_b128 v[172:175], v154 offset:1024
	ds_read_b128 v[176:179], v154 offset:2048
	ds_read_b128 v[180:183], v154 offset:3072
	s_add_u32 s38, s34, 0xfff00080
	s_addc_u32 s39, s35, -1
	s_cmp_eq_u32 s54, 60
	s_cselect_b32 s41, s23, s39
	s_cselect_b32 s40, s48, s38
	s_cselect_b32 s39, s21, s53
	s_cselect_b32 s38, s49, s52
	v_lshl_add_u64 v[148:149], s[34:35], 0, v[136:137]
	s_add_i32 m0, s29, 0xc000
	ds_read_b128 v[184:187], v155
	ds_read_b128 v[188:191], v155 offset:1024
	ds_read_b128 v[192:195], v155 offset:2048
	ds_read_b128 v[196:199], v155 offset:3072
	ds_read_b128 v[200:203], v155 offset:4096
	ds_read_b128 v[204:207], v155 offset:5120
	ds_read_b128 v[208:211], v155 offset:6144
	ds_read_b128 v[212:215], v155 offset:7168
	global_load_lds_dwordx4 v[148:149], off
	v_lshl_add_u64 v[148:149], s[34:35], 0, v[138:139]
	s_add_i32 m0, s29, 0xe000
	s_nop 0
	global_load_lds_dwordx4 v[148:149], off
	s_waitcnt vmcnt(8)
	s_waitcnt lgkmcnt(0)
	s_barrier
	s_setprio 1
	s_waitcnt lgkmcnt(0)
	v_mfma_f32_16x16x32_bf16 v[124:127], v[144:147], v[184:187], v[124:127]
	v_mfma_f32_16x16x32_bf16 v[120:123], v[160:163], v[184:187], v[120:123]
	v_mfma_f32_16x16x32_bf16 v[108:111], v[144:147], v[192:195], v[108:111]
	v_mfma_f32_16x16x32_bf16 v[104:107], v[160:163], v[192:195], v[104:107]
	v_mfma_f32_16x16x32_bf16 v[92:95], v[144:147], v[200:203], v[92:95]
	v_mfma_f32_16x16x32_bf16 v[88:91], v[160:163], v[200:203], v[88:91]
	v_mfma_f32_16x16x32_bf16 v[76:79], v[144:147], v[208:211], v[76:79]
	v_mfma_f32_16x16x32_bf16 v[72:75], v[160:163], v[208:211], v[72:75]
	v_mfma_f32_16x16x32_bf16 v[124:127], v[156:159], v[188:191], v[124:127]
	v_mfma_f32_16x16x32_bf16 v[120:123], v[164:167], v[188:191], v[120:123]
	v_mfma_f32_16x16x32_bf16 v[108:111], v[156:159], v[196:199], v[108:111]
	v_mfma_f32_16x16x32_bf16 v[104:107], v[164:167], v[196:199], v[104:107]
	v_mfma_f32_16x16x32_bf16 v[92:95], v[156:159], v[204:207], v[92:95]
	v_mfma_f32_16x16x32_bf16 v[88:91], v[164:167], v[204:207], v[88:91]
	v_mfma_f32_16x16x32_bf16 v[76:79], v[156:159], v[212:215], v[76:79]
	v_mfma_f32_16x16x32_bf16 v[72:75], v[164:167], v[212:215], v[72:75]
	v_mfma_f32_16x16x32_bf16 v[116:119], v[168:171], v[184:187], v[116:119]
	v_mfma_f32_16x16x32_bf16 v[112:115], v[176:179], v[184:187], v[112:115]
	v_mfma_f32_16x16x32_bf16 v[100:103], v[168:171], v[192:195], v[100:103]
	v_mfma_f32_16x16x32_bf16 v[96:99], v[176:179], v[192:195], v[96:99]
	v_mfma_f32_16x16x32_bf16 v[84:87], v[168:171], v[200:203], v[84:87]
	v_mfma_f32_16x16x32_bf16 v[80:83], v[176:179], v[200:203], v[80:83]
	v_mfma_f32_16x16x32_bf16 v[68:71], v[168:171], v[208:211], v[68:71]
	v_mfma_f32_16x16x32_bf16 v[64:67], v[176:179], v[208:211], v[64:67]
	v_mfma_f32_16x16x32_bf16 v[116:119], v[172:175], v[188:191], v[116:119]
	v_mfma_f32_16x16x32_bf16 v[112:115], v[180:183], v[188:191], v[112:115]
	v_mfma_f32_16x16x32_bf16 v[100:103], v[172:175], v[196:199], v[100:103]
	v_mfma_f32_16x16x32_bf16 v[96:99], v[180:183], v[196:199], v[96:99]
	v_mfma_f32_16x16x32_bf16 v[84:87], v[172:175], v[204:207], v[84:87]
	v_mfma_f32_16x16x32_bf16 v[80:83], v[180:183], v[204:207], v[80:83]
	v_mfma_f32_16x16x32_bf16 v[68:71], v[172:175], v[212:215], v[68:71]
	v_mfma_f32_16x16x32_bf16 v[64:67], v[180:183], v[212:215], v[64:67]
	s_setprio 0
	s_barrier
	s_add_i32 s55, s45, s3
	v_lshl_add_u64 v[148:149], s[38:39], 0, v[130:131]
	s_mov_b32 m0, s55
	ds_read_b128 v[184:187], v155 offset:16384
	ds_read_b128 v[188:191], v155 offset:17408
	ds_read_b128 v[192:195], v155 offset:18432
	ds_read_b128 v[196:199], v155 offset:19456
	ds_read_b128 v[200:203], v155 offset:20480
	ds_read_b128 v[204:207], v155 offset:21504
	ds_read_b128 v[208:211], v155 offset:22528
	ds_read_b128 v[212:215], v155 offset:23552
	global_load_lds_dwordx4 v[148:149], off
	s_add_i32 m0, s55, 0x2000
	s_add_u32 s56, s38, 0x100000
	v_lshl_add_u64 v[216:217], s[38:39], 0, v[134:135]
	s_addc_u32 s57, s39, 0
	s_add_i32 s55, s46, s3
	global_load_lds_dwordx4 v[216:217], off
	v_lshl_add_u64 v[218:219], s[56:57], 0, v[130:131]
	s_mov_b32 m0, s55
	v_lshl_add_u64 v[220:221], s[40:41], 0, v[132:133]
	global_load_lds_dwordx4 v[218:219], off
	v_lshl_add_u64 v[218:219], s[56:57], 0, v[134:135]
	s_add_i32 m0, s55, 0x2000
	s_nop 0
	global_load_lds_dwordx4 v[218:219], off
	v_lshl_add_u64 v[218:219], s[40:41], 0, v[128:129]
	s_mov_b32 m0, s29
	s_nop 0
	global_load_lds_dwordx4 v[218:219], off
	s_mov_b32 m0, s30
	s_nop 0
	global_load_lds_dwordx4 v[220:221], off
	s_waitcnt vmcnt(8)
	s_waitcnt lgkmcnt(0)
	s_barrier
; #define PG8_STAGE(bufoff, gbase, voff) do { _Pragma("unroll") for (int _i = 0; _i < 2; ++_i) \
;         __builtin_amdgcn_global_load_lds((const unsigned*)((const char*)(gbase) + (voff)[_i]), (PG8_LAS unsigned*)(lds + (bufoff) + ldsw + _i * 8192), 16, 0, 0); } while (0)
; #define PG8_LDA(dst, b, h) do { _Pragma("unroll") for (int m = 0; m < 4; ++m) _Pragma("unroll") for (int k = 0; k < 2; ++k) dst[m][k] = *(const PG8_LAS bf16x8*)(lds + PG8_SA(b, h) + aoff + m * 2048 + k * 1024); } while (0)
; #define PG8_LDB(dst, b, h) do { _Pragma("unroll") for (int n = 0; n < 2; ++n) _Pragma("unroll") for (int k = 0; k < 2; ++k) dst[n][k] = *(const PG8_LAS bf16x8*)(lds + PG8_SB(b, h) + boff + n * 2048 + k * 1024); } while (0)
; #define PG8_MMA(ai, bj, At, Bt) do { __builtin_amdgcn_s_setprio(1); _Pragma("unroll") for (int m = 0; m < 4; ++m) _Pragma("unroll") for (int n = 0; n < 2; ++n) _Pragma("unroll") for (int k = 0; k < 2; ++k) \
;         acc[ai][bj][m][n] = __builtin_amdgcn_mfma_f32_16x16x32_bf16(Bt[n][k], At[m][k], acc[ai][bj][m][n], 0, 0, 0); __builtin_amdgcn_s_setprio(0); } while (0)
; #define PG8_WAIT_V(n) asm volatile("s_waitcnt vmcnt(" #n ")" ::: "memory")
; #define PG8_WAIT_L(n) asm volatile("s_waitcnt lgkmcnt(" #n ")" ::: "memory")
; #define PG8_BAR __builtin_amdgcn_s_barrier()
; #define PG8_SCHED __builtin_amdgcn_sched_barrier(0)
; template <class Epi, class Sched, bool ALIGN_EPI = false, bool SP2 = false>
; __device__ __forceinline__ void gemm_phase(PG8_LAS unsigned char* lds, const Gemm g, const Sched& S, const Epi& E) {
;     ...
;             PG8_WAIT_V(8); PG8_WAIT_L(0); PG8_BAR; PG8_MMA(1, 0, At, B0); PG8_MMA(1, 1, At, B1); PG8_BAR; PG8_SCHED;
;             PG8_LDB(B0, 1, 0); PG8_LDB(B1, 1, 1); PG8_SCHED; PG8_LDA(At, 1, 0); PG8_STAGE(PG8_SA(0, 1), a2 + hstep, voffA);
;             PG8_WAIT_V(8); PG8_WAIT_L(0); PG8_BAR; PG8_MMA(0, 0, At, B0); PG8_MMA(0, 1, At, B1); PG8_BAR; PG8_SCHED;
	s_setprio 1
	s_waitcnt lgkmcnt(0)
	v_mfma_f32_16x16x32_bf16 v[60:63], v[144:147], v[184:187], v[60:63]
	v_mfma_f32_16x16x32_bf16 v[56:59], v[160:163], v[184:187], v[56:59]
	v_mfma_f32_16x16x32_bf16 v[44:47], v[144:147], v[192:195], v[44:47]
	v_mfma_f32_16x16x32_bf16 v[40:43], v[160:163], v[192:195], v[40:43]
	v_mfma_f32_16x16x32_bf16 v[28:31], v[144:147], v[200:203], v[28:31]
	v_mfma_f32_16x16x32_bf16 v[24:27], v[160:163], v[200:203], v[24:27]
	v_mfma_f32_16x16x32_bf16 v[12:15], v[144:147], v[208:211], v[12:15]
	v_mfma_f32_16x16x32_bf16 v[8:11], v[160:163], v[208:211], v[8:11]
	v_mfma_f32_16x16x32_bf16 v[60:63], v[156:159], v[188:191], v[60:63]
	v_mfma_f32_16x16x32_bf16 v[56:59], v[164:167], v[188:191], v[56:59]
	v_mfma_f32_16x16x32_bf16 v[44:47], v[156:159], v[196:199], v[44:47]
	v_mfma_f32_16x16x32_bf16 v[40:43], v[164:167], v[196:199], v[40:43]
	v_mfma_f32_16x16x32_bf16 v[28:31], v[156:159], v[204:207], v[28:31]
	v_mfma_f32_16x16x32_bf16 v[24:27], v[164:167], v[204:207], v[24:27]
	v_mfma_f32_16x16x32_bf16 v[12:15], v[156:159], v[212:215], v[12:15]
	v_mfma_f32_16x16x32_bf16 v[8:11], v[164:167], v[212:215], v[8:11]
	v_mfma_f32_16x16x32_bf16 v[52:55], v[168:171], v[184:187], v[52:55]
	v_mfma_f32_16x16x32_bf16 v[48:51], v[176:179], v[184:187], v[48:51]
	v_mfma_f32_16x16x32_bf16 v[36:39], v[168:171], v[192:195], v[36:39]
	v_mfma_f32_16x16x32_bf16 v[32:35], v[176:179], v[192:195], v[32:35]
	v_mfma_f32_16x16x32_bf16 v[20:23], v[168:171], v[200:203], v[20:23]
	v_mfma_f32_16x16x32_bf16 v[16:19], v[176:179], v[200:203], v[16:19]
	v_mfma_f32_16x16x32_bf16 v[4:7], v[168:171], v[208:211], v[4:7]
	v_mfma_f32_16x16x32_bf16 v[0:3], v[176:179], v[208:211], v[0:3]
	v_mfma_f32_16x16x32_bf16 v[52:55], v[172:175], v[188:191], v[52:55]
	v_mfma_f32_16x16x32_bf16 v[48:51], v[180:183], v[188:191], v[48:51]
	v_mfma_f32_16x16x32_bf16 v[36:39], v[172:175], v[196:199], v[36:39]
	v_mfma_f32_16x16x32_bf16 v[32:35], v[180:183], v[196:199], v[32:35]
	v_mfma_f32_16x16x32_bf16 v[20:23], v[172:175], v[204:207], v[20:23]
	v_mfma_f32_16x16x32_bf16 v[16:19], v[180:183], v[204:207], v[16:19]
	v_mfma_f32_16x16x32_bf16 v[4:7], v[172:175], v[212:215], v[4:7]
	v_mfma_f32_16x16x32_bf16 v[0:3], v[180:183], v[212:215], v[0:3]
	s_setprio 0
	s_barrier
	s_add_i32 s55, 0, 0x18000
	s_add_i32 s56, 0, 0x1c000
	v_add_u32_e32 v164, s55, v151
	v_add_u32_e32 v180, s56, v151
	ds_read_b128 v[144:147], v164
	ds_read_b128 v[156:159], v164 offset:1024
	ds_read_b128 v[160:163], v164 offset:2048
	ds_read_b128 v[164:167], v164 offset:3072
	ds_read_b128 v[168:171], v180
	ds_read_b128 v[172:175], v180 offset:1024
	ds_read_b128 v[176:179], v180 offset:2048
	ds_read_b128 v[180:183], v180 offset:3072
	s_add_u32 s40, s40, 0x100000
	s_addc_u32 s41, s41, 0
	s_mov_b32 m0, s31
	v_lshl_add_u64 v[222:223], s[40:41], 0, v[128:129]
	ds_read_b128 v[184:187], v155 offset:32768
	ds_read_b128 v[188:191], v155 offset:33792
	ds_read_b128 v[192:195], v155 offset:34816
	ds_read_b128 v[196:199], v155 offset:35840
	ds_read_b128 v[200:203], v155 offset:36864
	ds_read_b128 v[204:207], v155 offset:37888
	ds_read_b128 v[208:211], v155 offset:38912
	ds_read_b128 v[212:215], v155 offset:39936
	global_load_lds_dwordx4 v[222:223], off
	v_lshl_add_u64 v[222:223], s[40:41], 0, v[132:133]
	s_mov_b32 m0, s33
	s_nop 0
	global_load_lds_dwordx4 v[222:223], off
	s_waitcnt vmcnt(8)
	s_waitcnt lgkmcnt(0)
	s_barrier
	s_setprio 1
	s_waitcnt lgkmcnt(0)
	v_mfma_f32_16x16x32_bf16 v[124:127], v[144:147], v[184:187], v[124:127]
	v_mfma_f32_16x16x32_bf16 v[120:123], v[160:163], v[184:187], v[120:123]
	v_mfma_f32_16x16x32_bf16 v[108:111], v[144:147], v[192:195], v[108:111]
	v_mfma_f32_16x16x32_bf16 v[104:107], v[160:163], v[192:195], v[104:107]
	v_mfma_f32_16x16x32_bf16 v[92:95], v[144:147], v[200:203], v[92:95]
	v_mfma_f32_16x16x32_bf16 v[88:91], v[160:163], v[200:203], v[88:91]
	v_mfma_f32_16x16x32_bf16 v[76:79], v[144:147], v[208:211], v[76:79]
	v_mfma_f32_16x16x32_bf16 v[72:75], v[160:163], v[208:211], v[72:75]
	v_mfma_f32_16x16x32_bf16 v[124:127], v[156:159], v[188:191], v[124:127]
	v_mfma_f32_16x16x32_bf16 v[120:123], v[164:167], v[188:191], v[120:123]
	v_mfma_f32_16x16x32_bf16 v[108:111], v[156:159], v[196:199], v[108:111]
	v_mfma_f32_16x16x32_bf16 v[104:107], v[164:167], v[196:199], v[104:107]
	v_mfma_f32_16x16x32_bf16 v[92:95], v[156:159], v[204:207], v[92:95]
	v_mfma_f32_16x16x32_bf16 v[88:91], v[164:167], v[204:207], v[88:91]
	v_mfma_f32_16x16x32_bf16 v[76:79], v[156:159], v[212:215], v[76:79]
	v_mfma_f32_16x16x32_bf16 v[72:75], v[164:167], v[212:215], v[72:75]
	v_mfma_f32_16x16x32_bf16 v[116:119], v[168:171], v[184:187], v[116:119]
	v_mfma_f32_16x16x32_bf16 v[112:115], v[176:179], v[184:187], v[112:115]
	v_mfma_f32_16x16x32_bf16 v[100:103], v[168:171], v[192:195], v[100:103]
	v_mfma_f32_16x16x32_bf16 v[96:99], v[176:179], v[192:195], v[96:99]
	v_mfma_f32_16x16x32_bf16 v[84:87], v[168:171], v[200:203], v[84:87]
	v_mfma_f32_16x16x32_bf16 v[80:83], v[176:179], v[200:203], v[80:83]
	v_mfma_f32_16x16x32_bf16 v[68:71], v[168:171], v[208:211], v[68:71]
	v_mfma_f32_16x16x32_bf16 v[64:67], v[176:179], v[208:211], v[64:67]
	v_mfma_f32_16x16x32_bf16 v[116:119], v[172:175], v[188:191], v[116:119]
	v_mfma_f32_16x16x32_bf16 v[112:115], v[180:183], v[188:191], v[112:115]
	v_mfma_f32_16x16x32_bf16 v[100:103], v[172:175], v[196:199], v[100:103]
	v_mfma_f32_16x16x32_bf16 v[96:99], v[180:183], v[196:199], v[96:99]
	v_mfma_f32_16x16x32_bf16 v[84:87], v[172:175], v[204:207], v[84:87]
	v_mfma_f32_16x16x32_bf16 v[80:83], v[180:183], v[204:207], v[80:83]
	v_mfma_f32_16x16x32_bf16 v[68:71], v[172:175], v[212:215], v[68:71]
	v_mfma_f32_16x16x32_bf16 v[64:67], v[180:183], v[212:215], v[64:67]
	s_setprio 0
	s_barrier
; #define PG8_STAGE(bufoff, gbase, voff) do { _Pragma("unroll") for (int _i = 0; _i < 2; ++_i) \
;         __builtin_amdgcn_global_load_lds((const unsigned*)((const char*)(gbase) + (voff)[_i]), (PG8_LAS unsigned*)(lds + (bufoff) + ldsw + _i * 8192), 16, 0, 0); } while (0)
; #define PG8_LDA(dst, b, h) do { _Pragma("unroll") for (int m = 0; m < 4; ++m) _Pragma("unroll") for (int k = 0; k < 2; ++k) dst[m][k] = *(const PG8_LAS bf16x8*)(lds + PG8_SA(b, h) + aoff + m * 2048 + k * 1024); } while (0)
; #define PG8_MMA(ai, bj, At, Bt) do { __builtin_amdgcn_s_setprio(1); _Pragma("unroll") for (int m = 0; m < 4; ++m) _Pragma("unroll") for (int n = 0; n < 2; ++n) _Pragma("unroll") for (int k = 0; k < 2; ++k) \
;         acc[ai][bj][m][n] = __builtin_amdgcn_mfma_f32_16x16x32_bf16(Bt[n][k], At[m][k], acc[ai][bj][m][n], 0, 0, 0); __builtin_amdgcn_s_setprio(0); } while (0)
; #define PG8_WAIT_V(n) asm volatile("s_waitcnt vmcnt(" #n ")" ::: "memory")
; #define PG8_WAIT_L(n) asm volatile("s_waitcnt lgkmcnt(" #n ")" ::: "memory")
; #define PG8_BAR __builtin_amdgcn_s_barrier()
; #define PG8_SCHED __builtin_amdgcn_sched_barrier(0)
; template <class Epi, class Sched, bool ALIGN_EPI = false, bool SP2 = false>
; __device__ __forceinline__ void gemm_phase(PG8_LAS unsigned char* lds, const Gemm g, const Sched& S, const Epi& E) {
;     ...
;             PG8_LDA(At, 1, 1); PG8_STAGE(PG8_SB(1, 0), b3, voffB); PG8_STAGE(PG8_SB(1, 1), b3 + hstep, voffB); PG8_STAGE(PG8_SA(1, 0), a3, voffA);
;             PG8_WAIT_V(8); PG8_WAIT_L(0); PG8_BAR; PG8_MMA(1, 0, At, B0); PG8_MMA(1, 1, At, B1); PG8_BAR; PG8_SCHED;
	s_add_i32 s40, s55, s3
	v_lshl_add_u64 v[148:149], v[148:149], 0, s[6:7]
	s_mov_b32 m0, s40
	ds_read_b128 v[184:187], v155 offset:49152
	ds_read_b128 v[188:191], v155 offset:50176
	ds_read_b128 v[192:195], v155 offset:51200
	ds_read_b128 v[196:199], v155 offset:52224
	ds_read_b128 v[200:203], v155 offset:53248
	ds_read_b128 v[204:207], v155 offset:54272
	ds_read_b128 v[208:211], v155 offset:55296
	ds_read_b128 v[212:215], v155 offset:56320
	global_load_lds_dwordx4 v[148:149], off
	s_add_i32 m0, s40, 0x2000
	s_add_u32 s38, s38, 0x100080
	v_lshl_add_u64 v[148:149], v[216:217], 0, s[6:7]
	s_addc_u32 s39, s39, 0
	s_add_i32 s40, s56, s3
	global_load_lds_dwordx4 v[148:149], off
	v_lshl_add_u64 v[148:149], s[38:39], 0, v[130:131]
	s_mov_b32 m0, s40
	s_nop 0
	global_load_lds_dwordx4 v[148:149], off
	v_lshl_add_u64 v[148:149], s[38:39], 0, v[134:135]
	s_add_i32 m0, s40, 0x2000
	s_nop 0
	global_load_lds_dwordx4 v[148:149], off
	v_lshl_add_u64 v[148:149], v[218:219], 0, s[6:7]
	s_mov_b32 m0, s43
	s_nop 0
	global_load_lds_dwordx4 v[148:149], off
	v_lshl_add_u64 v[148:149], v[220:221], 0, s[6:7]
	s_mov_b32 m0, s44
	s_nop 0
	global_load_lds_dwordx4 v[148:149], off
	s_waitcnt vmcnt(8)
	s_waitcnt lgkmcnt(0)
	s_barrier
	s_setprio 1
	s_waitcnt lgkmcnt(0)
	v_mfma_f32_16x16x32_bf16 v[60:63], v[144:147], v[184:187], v[60:63]
	v_mfma_f32_16x16x32_bf16 v[56:59], v[160:163], v[184:187], v[56:59]
	v_mfma_f32_16x16x32_bf16 v[44:47], v[144:147], v[192:195], v[44:47]
	v_mfma_f32_16x16x32_bf16 v[40:43], v[160:163], v[192:195], v[40:43]
	v_mfma_f32_16x16x32_bf16 v[28:31], v[144:147], v[200:203], v[28:31]
	v_mfma_f32_16x16x32_bf16 v[24:27], v[160:163], v[200:203], v[24:27]
	v_mfma_f32_16x16x32_bf16 v[12:15], v[144:147], v[208:211], v[12:15]
	v_mfma_f32_16x16x32_bf16 v[8:11], v[160:163], v[208:211], v[8:11]
	v_mfma_f32_16x16x32_bf16 v[60:63], v[156:159], v[188:191], v[60:63]
	v_mfma_f32_16x16x32_bf16 v[56:59], v[164:167], v[188:191], v[56:59]
	v_mfma_f32_16x16x32_bf16 v[44:47], v[156:159], v[196:199], v[44:47]
	v_mfma_f32_16x16x32_bf16 v[40:43], v[164:167], v[196:199], v[40:43]
	v_mfma_f32_16x16x32_bf16 v[28:31], v[156:159], v[204:207], v[28:31]
	v_mfma_f32_16x16x32_bf16 v[24:27], v[164:167], v[204:207], v[24:27]
	v_mfma_f32_16x16x32_bf16 v[12:15], v[156:159], v[212:215], v[12:15]
	v_mfma_f32_16x16x32_bf16 v[8:11], v[164:167], v[212:215], v[8:11]
	v_mfma_f32_16x16x32_bf16 v[52:55], v[168:171], v[184:187], v[52:55]
	v_mfma_f32_16x16x32_bf16 v[48:51], v[176:179], v[184:187], v[48:51]
	v_mfma_f32_16x16x32_bf16 v[36:39], v[168:171], v[192:195], v[36:39]
	v_mfma_f32_16x16x32_bf16 v[32:35], v[176:179], v[192:195], v[32:35]
	v_mfma_f32_16x16x32_bf16 v[20:23], v[168:171], v[200:203], v[20:23]
	v_mfma_f32_16x16x32_bf16 v[16:19], v[176:179], v[200:203], v[16:19]
	v_mfma_f32_16x16x32_bf16 v[4:7], v[168:171], v[208:211], v[4:7]
	v_mfma_f32_16x16x32_bf16 v[0:3], v[176:179], v[208:211], v[0:3]
	v_mfma_f32_16x16x32_bf16 v[52:55], v[172:175], v[188:191], v[52:55]
	v_mfma_f32_16x16x32_bf16 v[48:51], v[180:183], v[188:191], v[48:51]
	v_mfma_f32_16x16x32_bf16 v[36:39], v[172:175], v[196:199], v[36:39]
	v_mfma_f32_16x16x32_bf16 v[32:35], v[180:183], v[196:199], v[32:35]
	v_mfma_f32_16x16x32_bf16 v[20:23], v[172:175], v[204:207], v[20:23]
	v_mfma_f32_16x16x32_bf16 v[16:19], v[180:183], v[204:207], v[16:19]
	v_mfma_f32_16x16x32_bf16 v[4:7], v[172:175], v[212:215], v[4:7]
	v_mfma_f32_16x16x32_bf16 v[0:3], v[180:183], v[212:215], v[0:3]
	s_setprio 0
	s_barrier
	s_add_i32 s54, s54, 2
	s_add_u32 s34, s34, 0x100
	s_addc_u32 s35, s35, 0
	s_add_u32 s52, s52, 0x100
	s_addc_u32 s53, s53, 0
	s_cmp_gt_u32 s54, 61
	s_cbranch_scc0 .LBB0_813
	s_and_b64 vcc, exec, s[10:11]
	s_cbranch_vccz .LBB0_816
	s_barrier
